# baseline (speedup 1.0000x reference)
; __device__ __forceinline__ int tid_opaque() { int t = threadIdx.x; asm volatile("" : "+v"(t)); return t; }
; #define BAR __builtin_amdgcn_s_barrier()
; template <bool SWAP, int lda, int ldb, int K>
; __device__ __forceinline__ void gemm256(const bf16_t* __restrict__ Ap, const bf16_t* __restrict__ Bp, f32x4 (&acc)[2][2][4][2]) {
;     ...
;     const int gtid = tid_opaque();
;     const int wid = gtid >> 6, lane = gtid & 63, wr = wid >> 2, wc = wid & 3, fr = lane & 15, fq = lane >> 4;
;     bf16x8 At[4][2], B0[2][2], B1[2][2];
;     constexpr int nt = K / BK;
;     unsigned offA[2], offB[2];
;     for (int _i = 0; _i < 2; ++_i) {
;         int _b = gtid * 16 + _i * 8192; int _r, _c; stage_rc(_b, _r, _c);
;         offA[_i] = (unsigned)(_r * lda + _c) * 2u; offB[_i] = (unsigned)(_r * ldb + _c) * 2u;
;     }
;     STAGE(SB(0, 0), Bp, ldb, 0, 0); STAGE(SA(0, 0), Ap, lda, 0, 0);
;     STAGE(SB(0, 1), Bp, ldb, HALF, 0); STAGE(SA(0, 1), Ap, lda, HALF, 0);
;     if (wr == 1) BAR;
.LBB0_374:
	v_mov_b32_e32 v136, v208
	s_cmp_eq_u32 s26, 1
	v_bfe_i32 v2, v136, 27, 1
	v_lshlrev_b32_e32 v0, 4, v136
	v_lshrrev_b32_e32 v2, 22, v2
	v_add_u32_e32 v2, v0, v2
	v_and_b32_e32 v2, 0xfffffc00, v2
	v_ashrrev_i32_e32 v1, 31, v136
	v_sub_u32_e32 v2, v0, v2
	v_lshrrev_b32_e32 v1, 26, v1
	v_lshrrev_b32_e32 v3, 4, v2
	v_add_u32_e32 v1, v136, v1
	v_bitop3_b32 v3, v3, v2, 32 bitop3:0x6c
	v_ashrrev_i32_e32 v2, 31, v2
	v_ashrrev_i32_e32 v1, 6, v1
	v_lshrrev_b32_e32 v2, 26, v2
	v_lshlrev_b32_e32 v4, 3, v1
	v_add_u32_e32 v2, v3, v2
	v_and_b32_e32 v4, -16, v4
	v_ashrrev_i32_e32 v2, 6, v2
	v_add_u32_e32 v4, v2, v4
	v_mul_i32_i24_e32 v2, 64, v2
	s_movk_i32 s0, 0xe00
	v_lshlrev_b32_e32 v1, 5, v1
	v_sub_u32_e32 v2, v3, v2
	s_cselect_b32 s2, 0x800, s0
	s_cmp_lg_u32 s26, 0
	v_and_b32_e32 v1, 32, v1
	v_ashrrev_i16_sdwa v2, v210, sext(v2) dst_sel:DWORD dst_unused:UNUSED_PAD src0_sel:DWORD src1_sel:BYTE_0
	s_cselect_b64 s[14:15], -1, 0
	v_add_u32_sdwa v1, v1, sext(v2) dst_sel:DWORD dst_unused:UNUSED_PAD src0_sel:DWORD src1_sel:WORD_0
	v_lshlrev_b32_e32 v2, 13, v4
	s_and_b64 s[0:1], s[14:15], exec
	v_lshl_add_u32 v128, v1, 1, v2
	v_add_u32_e32 v1, 0x2000, v0
	s_cselect_b32 s0, s2, 0x200
	v_ashrrev_i32_e32 v2, 31, v1
	s_lshl_b32 s19, s0, 1
	v_lshrrev_b32_e32 v2, 22, v2
	s_add_u32 s2, s21, s19
	v_add_u32_e32 v2, v1, v2
	s_addc_u32 s3, s22, 0
	s_lshl_b32 s18, s26, 10
	v_ashrrev_i32_e32 v2, 10, v2
	s_add_i32 s0, s18, s10
	v_mul_i32_i24_e32 v3, 0x400, v2
	s_ashr_i32 s1, s0, 31
	v_sub_u32_e32 v1, v1, v3
	s_lshl_b64 s[0:1], s[0:1], 10
	v_lshrrev_b32_e32 v3, 4, v1
	s_add_u32 s4, s33, s0
	v_bitop3_b32 v1, v3, v1, 32 bitop3:0x6c
	s_addc_u32 s5, s68, s1
	v_mad_u64_u32 v[130:131], s[0:1], v4, s95, v[128:129]
	v_ashrrev_i32_e32 v4, 31, v1
	v_lshrrev_b32_e32 v4, 26, v4
	v_add_u32_e32 v4, v1, v4
	v_lshlrev_b32_e32 v3, 3, v2
	v_ashrrev_i32_e32 v5, 6, v4
	v_and_b32_e32 v4, 0xc0, v4
	v_and_b32_e32 v3, -16, v3
	v_lshlrev_b32_e32 v2, 5, v2
	v_sub_u32_e32 v1, v1, v4
	v_add_u32_e32 v3, v5, v3
	v_and_b32_e32 v2, 32, v2
	v_ashrrev_i16_sdwa v1, v210, sext(v1) dst_sel:DWORD dst_unused:UNUSED_PAD src0_sel:DWORD src1_sel:BYTE_0
	v_add_u32_sdwa v1, v2, sext(v1) dst_sel:DWORD dst_unused:UNUSED_PAD src0_sel:DWORD src1_sel:WORD_0
	v_lshlrev_b32_e32 v2, 13, v3
	v_lshl_add_u32 v132, v1, 1, v2
	v_mad_u64_u32 v[134:135], s[0:1], v3, s95, v[132:133]
	v_add_u32_e32 v142, s90, v0
	v_add_u32_e32 v143, 0x2000, v142
	v_readfirstlane_b32 s0, v142
	s_mov_b32 m0, s0
	v_readfirstlane_b32 s0, v143
	v_add_u32_e32 v144, 0, v0
	global_load_lds_dwordx4 v130, s[4:5]
	s_mov_b32 m0, s0
	v_readfirstlane_b32 s0, v144
	v_add_u32_e32 v145, 0x2000, v144
	global_load_lds_dwordx4 v134, s[4:5]
	s_mov_b32 m0, s0
	v_readfirstlane_b32 s0, v145
	v_add_u32_e32 v147, s64, v0
	global_load_lds_dwordx4 v128, s[2:3]
	s_mov_b32 m0, s0
	s_add_u32 s6, s4, 0x20000
	v_readfirstlane_b32 s0, v147
	v_add_u32_e32 v148, 0x2000, v147
	global_load_lds_dwordx4 v132, s[2:3]
	s_addc_u32 s7, s5, 0
	s_mov_b32 m0, s0
	v_readfirstlane_b32 s0, v148
	v_add_u32_e32 v149, 0x4000, v144
	global_load_lds_dwordx4 v130, s[6:7]
	s_mov_b32 m0, s0
	s_add_u32 s0, s2, 0x100000
	v_readfirstlane_b32 s16, v149
	v_add_u32_e32 v150, 0x6000, v144
	global_load_lds_dwordx4 v134, s[6:7]
	s_addc_u32 s1, s3, 0
	s_mov_b32 m0, s16
	v_readfirstlane_b32 s16, v150
	global_load_lds_dwordx4 v128, s[0:1]
	s_mov_b32 m0, s16
	v_ashrrev_i32_e32 v1, 8, v136
	global_load_lds_dwordx4 v132, s[0:1]
	v_cmp_eq_u32_e32 vcc, 1, v1
	s_and_saveexec_b64 s[16:17], vcc
	s_cbranch_execz .LBB0_376
	s_barrier
	s_setprio 1

; #define LDA(dst, b, h) for (int m = 0; m < 4; ++m) for (int k = 0; k < 2; ++k) \
;     dst[m][k] = *reinterpret_cast<const bf16x8*>((char*)SA(b, h) + lds_byte(wr * 64 + m * 16 + fr, k * 32 + fq * 8))
; #define LDB(dst, b, h) for (int n = 0; n < 2; ++n) for (int k = 0; k < 2; ++k) \
;     dst[n][k] = *reinterpret_cast<const bf16x8*>((char*)SB(b, h) + lds_byte(wc * 32 + n * 16 + fr, k * 32 + fq * 8))
; #define WAIT_V(n) asm volatile("s_waitcnt vmcnt(" #n ")" ::: "memory")
; #define WAIT_L(n) asm volatile("s_waitcnt lgkmcnt(" #n ")" ::: "memory")
; #define BAR __builtin_amdgcn_s_barrier()
; #define SCHED __builtin_amdgcn_sched_barrier(0)
; template <bool SWAP, int lda, int ldb, int K>
; __device__ __forceinline__ void gemm256(const bf16_t* __restrict__ Ap, const bf16_t* __restrict__ Bp, f32x4 (&acc)[2][2][4][2]) {
;     ...
;     for (int t = 0; t < nt - 2; t += 2) {
;         LDB(B0, 0, 0); SCHED; LDA(At, 0, 0); STAGE(SA(1, 1), Ap, lda, HALF, t + 1);
;         WAIT_L(8); BAR; WAIT_L(0); MMA(0, 0, At, B0); BAR; SCHED;
;         LDB(B1, 0, 1); STAGE(SB(0, 0), Bp, ldb, 0, t + 2);
;         BAR; WAIT_L(0); MMA(0, 1, At, B1); BAR;
;         LDA(At, 0, 1); STAGE(SA(0, 0), Ap, lda, 0, t + 2);
;         BAR; WAIT_L(0); MMA(1, 0, At, B0); BAR; SCHED;
;         STAGE(SB(0, 1), Bp, ldb, HALF, t + 2);
;         WAIT_V(6); BAR; MMA(1, 1, At, B1); BAR;
.LBB0_377:
	ds_read_b128 v[162:165], v158
	ds_read_b128 v[166:169], v158 offset:1024
	ds_read_b128 v[170:173], v158 offset:2048
	ds_read_b128 v[174:177], v158 offset:3072
	s_add_u32 s29, s19, s0
	s_addc_u32 s31, s27, s1
	s_add_u32 s30, s29, 0x80
	v_add_u32_e32 v159, 0xc000, v144
	s_addc_u32 s31, s31, 0
	v_readfirstlane_b32 s29, v159
	v_lshl_add_u64 v[160:161], s[30:31], 0, v[128:129]
	s_mov_b32 m0, s29
	ds_read_b128 v[178:181], v140
	ds_read_b128 v[182:185], v140 offset:1024
	ds_read_b128 v[186:189], v139
	ds_read_b128 v[190:193], v139 offset:1024
	ds_read_b128 v[194:197], v138
	ds_read_b128 v[198:201], v138 offset:1024
	ds_read_b128 v[202:205], v137
	ds_read_b128 v[214:217], v137 offset:1024
	global_load_lds_dwordx4 v[160:161], off
	v_add_u32_e32 v160, 0xe000, v144
	v_lshl_add_u64 v[206:207], s[30:31], 0, v[132:133]
	v_readfirstlane_b32 s29, v160
	s_mov_b32 m0, s29
	s_nop 0
	global_load_lds_dwordx4 v[206:207], off
	s_waitcnt lgkmcnt(8)
	s_barrier
	s_waitcnt lgkmcnt(0)
	s_nop 0
	s_waitcnt lgkmcnt(0)
	v_mfma_f32_16x16x32_bf16 v[124:127], v[162:165], v[178:181], v[124:127]
	v_mfma_f32_16x16x32_bf16 v[120:123], v[170:173], v[178:181], v[120:123]
	v_mfma_f32_16x16x32_bf16 v[116:119], v[162:165], v[186:189], v[116:119]
	v_mfma_f32_16x16x32_bf16 v[112:115], v[170:173], v[186:189], v[112:115]
	v_mfma_f32_16x16x32_bf16 v[108:111], v[162:165], v[194:197], v[108:111]
	v_mfma_f32_16x16x32_bf16 v[104:107], v[170:173], v[194:197], v[104:107]
	v_mfma_f32_16x16x32_bf16 v[100:103], v[162:165], v[202:205], v[100:103]
	v_mfma_f32_16x16x32_bf16 v[96:99], v[170:173], v[202:205], v[96:99]
	v_mfma_f32_16x16x32_bf16 v[124:127], v[166:169], v[182:185], v[124:127]
	v_mfma_f32_16x16x32_bf16 v[120:123], v[174:177], v[182:185], v[120:123]
	v_mfma_f32_16x16x32_bf16 v[116:119], v[166:169], v[190:193], v[116:119]
	v_mfma_f32_16x16x32_bf16 v[112:115], v[174:177], v[190:193], v[112:115]
	v_mfma_f32_16x16x32_bf16 v[108:111], v[166:169], v[198:201], v[108:111]
	v_mfma_f32_16x16x32_bf16 v[104:107], v[174:177], v[198:201], v[104:107]
	v_mfma_f32_16x16x32_bf16 v[100:103], v[166:169], v[214:217], v[100:103]
	v_mfma_f32_16x16x32_bf16 v[96:99], v[174:177], v[214:217], v[96:99]
	s_nop 0
	s_barrier
	s_add_u32 s29, s4, s0
	s_addc_u32 s34, s5, s1
	s_add_u32 s30, s29, 0x100
	s_addc_u32 s31, s34, 0
	v_readfirstlane_b32 s35, v142
	v_lshl_add_u64 v[206:207], s[30:31], 0, v[130:131]
	s_mov_b32 m0, s35
	ds_read_b128 v[218:221], v154
	ds_read_b128 v[222:225], v154 offset:1024
	ds_read_b128 v[226:229], v154 offset:2048
	ds_read_b128 v[230:233], v154 offset:3072
	global_load_lds_dwordx4 v[206:207], off
	v_lshl_add_u64 v[206:207], s[30:31], 0, v[134:135]
	v_readfirstlane_b32 s30, v143
	s_mov_b32 m0, s30
	s_nop 0
	global_load_lds_dwordx4 v[206:207], off
	s_barrier
	s_waitcnt lgkmcnt(0)
	s_nop 0
	s_waitcnt lgkmcnt(0)
	v_mfma_f32_16x16x32_bf16 v[92:95], v[218:221], v[178:181], v[92:95]
	v_mfma_f32_16x16x32_bf16 v[88:91], v[226:229], v[178:181], v[88:91]
	v_mfma_f32_16x16x32_bf16 v[84:87], v[218:221], v[186:189], v[84:87]
	v_mfma_f32_16x16x32_bf16 v[80:83], v[226:229], v[186:189], v[80:83]
	v_mfma_f32_16x16x32_bf16 v[76:79], v[218:221], v[194:197], v[76:79]
	v_mfma_f32_16x16x32_bf16 v[72:75], v[226:229], v[194:197], v[72:75]
	v_mfma_f32_16x16x32_bf16 v[68:71], v[218:221], v[202:205], v[68:71]
	v_mfma_f32_16x16x32_bf16 v[64:67], v[226:229], v[202:205], v[64:67]
	v_mfma_f32_16x16x32_bf16 v[92:95], v[222:225], v[182:185], v[92:95]
	v_mfma_f32_16x16x32_bf16 v[88:91], v[230:233], v[182:185], v[88:91]
	v_mfma_f32_16x16x32_bf16 v[84:87], v[222:225], v[190:193], v[84:87]
	v_mfma_f32_16x16x32_bf16 v[80:83], v[230:233], v[190:193], v[80:83]
	v_mfma_f32_16x16x32_bf16 v[76:79], v[222:225], v[198:201], v[76:79]
	v_mfma_f32_16x16x32_bf16 v[72:75], v[230:233], v[198:201], v[72:75]
	v_mfma_f32_16x16x32_bf16 v[68:71], v[222:225], v[214:217], v[68:71]
	v_mfma_f32_16x16x32_bf16 v[64:67], v[230:233], v[214:217], v[64:67]
	s_nop 0
	s_add_u32 s35, s2, s0
	s_addc_u32 s36, s3, s1
	s_add_u32 s30, s35, 0x100
	s_addc_u32 s31, s36, 0
	v_readfirstlane_b32 s37, v144
	v_lshl_add_u64 v[206:207], s[30:31], 0, v[128:129]
	s_mov_b32 m0, s37
	s_barrier
	ds_read_b128 v[178:181], v140 offset:16384
	ds_read_b128 v[182:185], v140 offset:17408
	ds_read_b128 v[186:189], v139 offset:16384
	ds_read_b128 v[190:193], v139 offset:17408
	ds_read_b128 v[194:197], v138 offset:16384
	ds_read_b128 v[198:201], v138 offset:17408
	ds_read_b128 v[202:205], v137 offset:16384
	ds_read_b128 v[214:217], v137 offset:17408
	global_load_lds_dwordx4 v[206:207], off
	v_lshl_add_u64 v[206:207], s[30:31], 0, v[132:133]
	v_readfirstlane_b32 s30, v145
	s_mov_b32 m0, s30
	s_nop 0
	global_load_lds_dwordx4 v[206:207], off
	s_barrier
	s_waitcnt lgkmcnt(0)
	s_nop 0
	s_waitcnt lgkmcnt(0)
	v_mfma_f32_16x16x32_bf16 v[60:63], v[162:165], v[178:181], v[60:63]
	v_mfma_f32_16x16x32_bf16 v[56:59], v[170:173], v[178:181], v[56:59]
	v_mfma_f32_16x16x32_bf16 v[52:55], v[162:165], v[186:189], v[52:55]
	v_mfma_f32_16x16x32_bf16 v[48:51], v[170:173], v[186:189], v[48:51]
	v_mfma_f32_16x16x32_bf16 v[44:47], v[162:165], v[194:197], v[44:47]
	v_mfma_f32_16x16x32_bf16 v[40:43], v[170:173], v[194:197], v[40:43]
	v_mfma_f32_16x16x32_bf16 v[36:39], v[162:165], v[202:205], v[36:39]
	v_mfma_f32_16x16x32_bf16 v[32:35], v[170:173], v[202:205], v[32:35]
	v_mfma_f32_16x16x32_bf16 v[60:63], v[166:169], v[182:185], v[60:63]
	v_mfma_f32_16x16x32_bf16 v[56:59], v[174:177], v[182:185], v[56:59]
	v_mfma_f32_16x16x32_bf16 v[52:55], v[166:169], v[190:193], v[52:55]
	v_mfma_f32_16x16x32_bf16 v[48:51], v[174:177], v[190:193], v[48:51]
	v_mfma_f32_16x16x32_bf16 v[44:47], v[166:169], v[198:201], v[44:47]
	v_mfma_f32_16x16x32_bf16 v[40:43], v[174:177], v[198:201], v[40:43]
	v_mfma_f32_16x16x32_bf16 v[36:39], v[166:169], v[214:217], v[36:39]
	v_mfma_f32_16x16x32_bf16 v[32:35], v[174:177], v[214:217], v[32:35]
	s_nop 0
	s_barrier
; #define LDA(dst, b, h) for (int m = 0; m < 4; ++m) for (int k = 0; k < 2; ++k) \
;     dst[m][k] = *reinterpret_cast<const bf16x8*>((char*)SA(b, h) + lds_byte(wr * 64 + m * 16 + fr, k * 32 + fq * 8))
; #define LDB(dst, b, h) for (int n = 0; n < 2; ++n) for (int k = 0; k < 2; ++k) \
;     dst[n][k] = *reinterpret_cast<const bf16x8*>((char*)SB(b, h) + lds_byte(wc * 32 + n * 16 + fr, k * 32 + fq * 8))
; #define WAIT_V(n) asm volatile("s_waitcnt vmcnt(" #n ")" ::: "memory")
; #define WAIT_L(n) asm volatile("s_waitcnt lgkmcnt(" #n ")" ::: "memory")
; #define BAR __builtin_amdgcn_s_barrier()
; #define SCHED __builtin_amdgcn_sched_barrier(0)
; template <bool SWAP, int lda, int ldb, int K>
; __device__ __forceinline__ void gemm256(const bf16_t* __restrict__ Ap, const bf16_t* __restrict__ Bp, f32x4 (&acc)[2][2][4][2]) {
;     ...
;         WAIT_V(6); BAR; MMA(1, 1, At, B1); BAR;
;         LDB(B0, 1, 0); SCHED; LDA(At, 1, 0); STAGE(SA(0, 1), Ap, lda, HALF, t + 2);
;         WAIT_L(8); BAR; WAIT_L(0); MMA(0, 0, At, B0); BAR; SCHED;
;         LDB(B1, 1, 1); STAGE(SB(1, 0), Bp, ldb, 0, t + 3);
;         BAR; WAIT_L(0); MMA(0, 1, At, B1); BAR;
;         LDA(At, 1, 1); STAGE(SA(1, 0), Ap, lda, 0, t + 3);
;         BAR; WAIT_L(0); MMA(1, 0, At, B0); BAR; SCHED;
	s_add_u32 s37, s6, s0
	s_addc_u32 s38, s7, s1
	s_add_u32 s30, s37, 0x100
	s_addc_u32 s31, s38, 0
	v_readfirstlane_b32 s39, v147
	v_lshl_add_u64 v[162:163], s[30:31], 0, v[130:131]
	s_mov_b32 m0, s39
	s_nop 0
	global_load_lds_dwordx4 v[162:163], off
	v_lshl_add_u64 v[162:163], s[30:31], 0, v[134:135]
	v_readfirstlane_b32 s30, v148
	s_mov_b32 m0, s30
	s_nop 0
	global_load_lds_dwordx4 v[162:163], off
	s_waitcnt vmcnt(6)
	s_barrier
	s_nop 0
	v_mfma_f32_16x16x32_bf16 v[28:31], v[218:221], v[178:181], v[28:31]
	v_mfma_f32_16x16x32_bf16 v[24:27], v[226:229], v[178:181], v[24:27]
	v_mfma_f32_16x16x32_bf16 v[20:23], v[218:221], v[186:189], v[20:23]
	v_mfma_f32_16x16x32_bf16 v[16:19], v[226:229], v[186:189], v[16:19]
	v_mfma_f32_16x16x32_bf16 v[12:15], v[218:221], v[194:197], v[12:15]
	v_mfma_f32_16x16x32_bf16 v[8:11], v[226:229], v[194:197], v[8:11]
	v_mfma_f32_16x16x32_bf16 v[4:7], v[218:221], v[202:205], v[4:7]
	v_mfma_f32_16x16x32_bf16 v[0:3], v[226:229], v[202:205], v[0:3]
	v_mfma_f32_16x16x32_bf16 v[28:31], v[222:225], v[182:185], v[28:31]
	v_mfma_f32_16x16x32_bf16 v[24:27], v[230:233], v[182:185], v[24:27]
	v_mfma_f32_16x16x32_bf16 v[20:23], v[222:225], v[190:193], v[20:23]
	v_mfma_f32_16x16x32_bf16 v[16:19], v[230:233], v[190:193], v[16:19]
	v_mfma_f32_16x16x32_bf16 v[12:15], v[222:225], v[198:201], v[12:15]
	v_mfma_f32_16x16x32_bf16 v[8:11], v[230:233], v[198:201], v[8:11]
	v_mfma_f32_16x16x32_bf16 v[4:7], v[222:225], v[214:217], v[4:7]
	v_mfma_f32_16x16x32_bf16 v[0:3], v[230:233], v[214:217], v[0:3]
	s_nop 0
	s_barrier
	ds_read_b128 v[162:165], v146
	ds_read_b128 v[166:169], v146 offset:1024
	ds_read_b128 v[170:173], v146 offset:2048
	ds_read_b128 v[174:177], v146 offset:3072
	s_add_u32 s30, s16, s0
	s_addc_u32 s31, s17, s1
	v_readfirstlane_b32 s39, v149
	v_lshl_add_u64 v[206:207], s[30:31], 0, v[128:129]
	s_mov_b32 m0, s39
	ds_read_b128 v[178:181], v140 offset:32768
	ds_read_b128 v[182:185], v140 offset:33792
	ds_read_b128 v[186:189], v139 offset:32768
	ds_read_b128 v[190:193], v139 offset:33792
	ds_read_b128 v[194:197], v138 offset:32768
	ds_read_b128 v[198:201], v138 offset:33792
	ds_read_b128 v[202:205], v137 offset:32768
	ds_read_b128 v[214:217], v137 offset:33792
	global_load_lds_dwordx4 v[206:207], off
	v_lshl_add_u64 v[206:207], s[30:31], 0, v[132:133]
	v_readfirstlane_b32 s30, v150
	s_mov_b32 m0, s30
	s_nop 0
	global_load_lds_dwordx4 v[206:207], off
	s_waitcnt lgkmcnt(8)
	s_barrier
	s_waitcnt lgkmcnt(0)
	s_nop 0
	s_waitcnt lgkmcnt(0)
	v_mfma_f32_16x16x32_bf16 v[124:127], v[162:165], v[178:181], v[124:127]
	v_mfma_f32_16x16x32_bf16 v[120:123], v[170:173], v[178:181], v[120:123]
	v_mfma_f32_16x16x32_bf16 v[116:119], v[162:165], v[186:189], v[116:119]
	v_mfma_f32_16x16x32_bf16 v[112:115], v[170:173], v[186:189], v[112:115]
	v_mfma_f32_16x16x32_bf16 v[108:111], v[162:165], v[194:197], v[108:111]
	v_mfma_f32_16x16x32_bf16 v[104:107], v[170:173], v[194:197], v[104:107]
	v_mfma_f32_16x16x32_bf16 v[100:103], v[162:165], v[202:205], v[100:103]
	v_mfma_f32_16x16x32_bf16 v[96:99], v[170:173], v[202:205], v[96:99]
	v_mfma_f32_16x16x32_bf16 v[124:127], v[166:169], v[182:185], v[124:127]
	v_mfma_f32_16x16x32_bf16 v[120:123], v[174:177], v[182:185], v[120:123]
	v_mfma_f32_16x16x32_bf16 v[116:119], v[166:169], v[190:193], v[116:119]
	v_mfma_f32_16x16x32_bf16 v[112:115], v[174:177], v[190:193], v[112:115]
	v_mfma_f32_16x16x32_bf16 v[108:111], v[166:169], v[198:201], v[108:111]
	v_mfma_f32_16x16x32_bf16 v[104:107], v[174:177], v[198:201], v[104:107]
	v_mfma_f32_16x16x32_bf16 v[100:103], v[166:169], v[214:217], v[100:103]
	v_mfma_f32_16x16x32_bf16 v[96:99], v[174:177], v[214:217], v[96:99]
	s_nop 0
	s_barrier
	s_add_u32 s30, s29, 0x180
	s_addc_u32 s31, s34, 0
	v_readfirstlane_b32 s29, v151
	v_lshl_add_u64 v[206:207], s[30:31], 0, v[130:131]
	s_mov_b32 m0, s29
	v_readfirstlane_b32 s29, v152
	ds_read_b128 v[218:221], v141
	ds_read_b128 v[222:225], v141 offset:1024
	ds_read_b128 v[226:229], v141 offset:2048
	ds_read_b128 v[230:233], v141 offset:3072
	global_load_lds_dwordx4 v[206:207], off
	v_lshl_add_u64 v[206:207], s[30:31], 0, v[134:135]
	s_mov_b32 m0, s29
	s_nop 0
	global_load_lds_dwordx4 v[206:207], off
	s_barrier
	s_waitcnt lgkmcnt(0)
	s_nop 0
	s_waitcnt lgkmcnt(0)
	v_mfma_f32_16x16x32_bf16 v[92:95], v[218:221], v[178:181], v[92:95]
	v_mfma_f32_16x16x32_bf16 v[88:91], v[226:229], v[178:181], v[88:91]
	v_mfma_f32_16x16x32_bf16 v[84:87], v[218:221], v[186:189], v[84:87]
	v_mfma_f32_16x16x32_bf16 v[80:83], v[226:229], v[186:189], v[80:83]
	v_mfma_f32_16x16x32_bf16 v[76:79], v[218:221], v[194:197], v[76:79]
	v_mfma_f32_16x16x32_bf16 v[72:75], v[226:229], v[194:197], v[72:75]
	v_mfma_f32_16x16x32_bf16 v[68:71], v[218:221], v[202:205], v[68:71]
	v_mfma_f32_16x16x32_bf16 v[64:67], v[226:229], v[202:205], v[64:67]
	v_mfma_f32_16x16x32_bf16 v[92:95], v[222:225], v[182:185], v[92:95]
	v_mfma_f32_16x16x32_bf16 v[88:91], v[230:233], v[182:185], v[88:91]
	v_mfma_f32_16x16x32_bf16 v[84:87], v[222:225], v[190:193], v[84:87]
	v_mfma_f32_16x16x32_bf16 v[80:83], v[230:233], v[190:193], v[80:83]
	v_mfma_f32_16x16x32_bf16 v[76:79], v[222:225], v[198:201], v[76:79]
	v_mfma_f32_16x16x32_bf16 v[72:75], v[230:233], v[198:201], v[72:75]
	v_mfma_f32_16x16x32_bf16 v[68:71], v[222:225], v[214:217], v[68:71]
	v_mfma_f32_16x16x32_bf16 v[64:67], v[230:233], v[214:217], v[64:67]
	s_nop 0
	s_add_u32 s30, s35, 0x180
	s_addc_u32 s31, s36, 0
	v_readfirstlane_b32 s29, v153
	v_lshl_add_u64 v[206:207], s[30:31], 0, v[128:129]
	s_mov_b32 m0, s29
	v_readfirstlane_b32 s29, v155
	s_barrier
; #define LDA(dst, b, h) for (int m = 0; m < 4; ++m) for (int k = 0; k < 2; ++k) \
;     dst[m][k] = *reinterpret_cast<const bf16x8*>((char*)SA(b, h) + lds_byte(wr * 64 + m * 16 + fr, k * 32 + fq * 8))
; #define LDB(dst, b, h) for (int n = 0; n < 2; ++n) for (int k = 0; k < 2; ++k) \
;     dst[n][k] = *reinterpret_cast<const bf16x8*>((char*)SB(b, h) + lds_byte(wc * 32 + n * 16 + fr, k * 32 + fq * 8))
; #define WAIT_V(n) asm volatile("s_waitcnt vmcnt(" #n ")" ::: "memory")
; #define WAIT_L(n) asm volatile("s_waitcnt lgkmcnt(" #n ")" ::: "memory")
; #define BAR __builtin_amdgcn_s_barrier()
; #define SCHED __builtin_amdgcn_sched_barrier(0)
; template <bool SWAP, int lda, int ldb, int K>
; __device__ __forceinline__ void gemm256(const bf16_t* __restrict__ Ap, const bf16_t* __restrict__ Bp, f32x4 (&acc)[2][2][4][2]) {
;     ...
;         LDA(At, 1, 1); STAGE(SA(1, 0), Ap, lda, 0, t + 3);
;         BAR; WAIT_L(0); MMA(1, 0, At, B0); BAR; SCHED;
;         STAGE(SB(1, 1), Bp, ldb, HALF, t + 3);
;         WAIT_V(6); BAR; MMA(1, 1, At, B1); BAR;
;     }
;     { LDB(B0, 0, 0); LDA(At, 0, 0); STAGE(SA(1, 1), Ap, lda, HALF, nt - 1);
;       BAR; WAIT_L(0); MMA(0, 0, At, B0); BAR;
;       LDB(B1, 0, 1); BAR; WAIT_L(0); MMA(0, 1, At, B1); BAR;
;       LDA(At, 0, 1); WAIT_V(4); BAR; WAIT_L(0); MMA(1, 0, At, B0); MMA(1, 1, At, B1); BAR; }
	ds_read_b128 v[178:181], v140 offset:49152
	ds_read_b128 v[182:185], v140 offset:50176
	ds_read_b128 v[186:189], v139 offset:49152
	ds_read_b128 v[190:193], v139 offset:50176
	ds_read_b128 v[194:197], v138 offset:49152
	ds_read_b128 v[198:201], v138 offset:50176
	ds_read_b128 v[202:205], v137 offset:49152
	ds_read_b128 v[214:217], v137 offset:50176
	global_load_lds_dwordx4 v[206:207], off
	v_lshl_add_u64 v[206:207], s[30:31], 0, v[132:133]
	s_mov_b32 m0, s29
	s_nop 0
	global_load_lds_dwordx4 v[206:207], off
	s_barrier
	s_waitcnt lgkmcnt(0)
	s_nop 0
	s_waitcnt lgkmcnt(0)
	v_mfma_f32_16x16x32_bf16 v[60:63], v[162:165], v[178:181], v[60:63]
	v_mfma_f32_16x16x32_bf16 v[56:59], v[170:173], v[178:181], v[56:59]
	v_mfma_f32_16x16x32_bf16 v[52:55], v[162:165], v[186:189], v[52:55]
	v_mfma_f32_16x16x32_bf16 v[48:51], v[170:173], v[186:189], v[48:51]
	v_mfma_f32_16x16x32_bf16 v[44:47], v[162:165], v[194:197], v[44:47]
	v_mfma_f32_16x16x32_bf16 v[40:43], v[170:173], v[194:197], v[40:43]
	v_mfma_f32_16x16x32_bf16 v[36:39], v[162:165], v[202:205], v[36:39]
	v_mfma_f32_16x16x32_bf16 v[32:35], v[170:173], v[202:205], v[32:35]
	v_mfma_f32_16x16x32_bf16 v[60:63], v[166:169], v[182:185], v[60:63]
	v_mfma_f32_16x16x32_bf16 v[56:59], v[174:177], v[182:185], v[56:59]
	v_mfma_f32_16x16x32_bf16 v[52:55], v[166:169], v[190:193], v[52:55]
	v_mfma_f32_16x16x32_bf16 v[48:51], v[174:177], v[190:193], v[48:51]
	v_mfma_f32_16x16x32_bf16 v[44:47], v[166:169], v[198:201], v[44:47]
	v_mfma_f32_16x16x32_bf16 v[40:43], v[174:177], v[198:201], v[40:43]
	v_mfma_f32_16x16x32_bf16 v[36:39], v[166:169], v[214:217], v[36:39]
	v_mfma_f32_16x16x32_bf16 v[32:35], v[174:177], v[214:217], v[32:35]
	s_nop 0
	s_barrier
	s_add_u32 s30, s37, 0x180
	s_addc_u32 s31, s38, 0
	v_readfirstlane_b32 s29, v156
	v_lshl_add_u64 v[162:163], s[30:31], 0, v[130:131]
	s_mov_b32 m0, s29
	v_readfirstlane_b32 s29, v157
	global_load_lds_dwordx4 v[162:163], off
	v_lshl_add_u64 v[162:163], s[30:31], 0, v[134:135]
	s_mov_b32 m0, s29
	s_nop 0
	global_load_lds_dwordx4 v[162:163], off
	s_waitcnt vmcnt(6)
	s_barrier
	s_nop 0
	v_mfma_f32_16x16x32_bf16 v[28:31], v[218:221], v[178:181], v[28:31]
	v_mfma_f32_16x16x32_bf16 v[24:27], v[226:229], v[178:181], v[24:27]
	v_mfma_f32_16x16x32_bf16 v[20:23], v[218:221], v[186:189], v[20:23]
	v_mfma_f32_16x16x32_bf16 v[16:19], v[226:229], v[186:189], v[16:19]
	v_mfma_f32_16x16x32_bf16 v[12:15], v[218:221], v[194:197], v[12:15]
	v_mfma_f32_16x16x32_bf16 v[8:11], v[226:229], v[194:197], v[8:11]
	v_mfma_f32_16x16x32_bf16 v[4:7], v[218:221], v[202:205], v[4:7]
	v_mfma_f32_16x16x32_bf16 v[0:3], v[226:229], v[202:205], v[0:3]
	v_mfma_f32_16x16x32_bf16 v[28:31], v[222:225], v[182:185], v[28:31]
	v_mfma_f32_16x16x32_bf16 v[24:27], v[230:233], v[182:185], v[24:27]
	v_mfma_f32_16x16x32_bf16 v[20:23], v[222:225], v[190:193], v[20:23]
	v_mfma_f32_16x16x32_bf16 v[16:19], v[230:233], v[190:193], v[16:19]
	v_mfma_f32_16x16x32_bf16 v[12:15], v[222:225], v[198:201], v[12:15]
	v_mfma_f32_16x16x32_bf16 v[8:11], v[230:233], v[198:201], v[8:11]
	v_mfma_f32_16x16x32_bf16 v[4:7], v[222:225], v[214:217], v[4:7]
	v_mfma_f32_16x16x32_bf16 v[0:3], v[230:233], v[214:217], v[0:3]
	s_nop 0
	s_add_i32 s28, s28, 2
	s_add_u32 s0, s0, 0x100
	s_addc_u32 s1, s1, 0
	s_cmp_lt_u32 s28, 4
	s_barrier
	s_cbranch_scc1 .LBB0_377
	s_add_u32 s0, s2, 0x100380
	s_addc_u32 s1, s3, 0
	v_readfirstlane_b32 s2, v159
	v_lshl_add_u64 v[130:131], s[0:1], 0, v[128:129]
	s_mov_b32 m0, s2
	ds_read_b128 v[142:145], v158
	ds_read_b128 v[148:151], v158 offset:1024
	ds_read_b128 v[162:165], v158 offset:2048
	ds_read_b128 v[166:169], v158 offset:3072
	ds_read_b128 v[170:173], v140
	ds_read_b128 v[174:177], v140 offset:1024
	ds_read_b128 v[178:181], v139
	ds_read_b128 v[182:185], v139 offset:1024
	ds_read_b128 v[186:189], v138
	ds_read_b128 v[190:193], v138 offset:1024
	ds_read_b128 v[194:197], v137
	ds_read_b128 v[198:201], v137 offset:1024
	global_load_lds_dwordx4 v[130:131], off
	v_lshl_add_u64 v[130:131], s[0:1], 0, v[132:133]
	v_readfirstlane_b32 s0, v160
	s_mov_b32 m0, s0
	s_nop 0
	global_load_lds_dwordx4 v[130:131], off
	s_barrier
	s_waitcnt lgkmcnt(0)
	s_nop 0
	s_waitcnt lgkmcnt(0)
	v_mfma_f32_16x16x32_bf16 v[124:127], v[142:145], v[170:173], v[124:127]
	v_mfma_f32_16x16x32_bf16 v[120:123], v[162:165], v[170:173], v[120:123]
	v_mfma_f32_16x16x32_bf16 v[116:119], v[142:145], v[178:181], v[116:119]
	v_mfma_f32_16x16x32_bf16 v[112:115], v[162:165], v[178:181], v[112:115]
	v_mfma_f32_16x16x32_bf16 v[108:111], v[142:145], v[186:189], v[108:111]
	v_mfma_f32_16x16x32_bf16 v[124:127], v[148:151], v[174:177], v[124:127]
	v_mfma_f32_16x16x32_bf16 v[120:123], v[166:169], v[174:177], v[120:123]
	v_mfma_f32_16x16x32_bf16 v[116:119], v[148:151], v[182:185], v[116:119]
	v_mfma_f32_16x16x32_bf16 v[112:115], v[166:169], v[182:185], v[112:115]
	v_mfma_f32_16x16x32_bf16 v[108:111], v[148:151], v[190:193], v[108:111]
	v_mfma_f32_16x16x32_bf16 v[104:107], v[162:165], v[186:189], v[104:107]
	v_mfma_f32_16x16x32_bf16 v[100:103], v[142:145], v[194:197], v[100:103]
	v_mfma_f32_16x16x32_bf16 v[96:99], v[162:165], v[194:197], v[96:99]
	v_mfma_f32_16x16x32_bf16 v[130:133], v[166:169], v[190:193], v[104:107]
	v_mfma_f32_16x16x32_bf16 v[156:159], v[148:151], v[198:201], v[100:103]
	v_mfma_f32_16x16x32_bf16 v[202:205], v[166:169], v[198:201], v[96:99]
	s_nop 0
	s_barrier
	s_nop 2
	ds_read_b128 v[96:99], v154
	ds_read_b128 v[100:103], v154 offset:1024
	ds_read_b128 v[104:107], v154 offset:2048
	ds_read_b128 v[152:155], v154 offset:3072
	s_barrier
; #define LDA(dst, b, h) for (int m = 0; m < 4; ++m) for (int k = 0; k < 2; ++k) \
;     dst[m][k] = *reinterpret_cast<const bf16x8*>((char*)SA(b, h) + lds_byte(wr * 64 + m * 16 + fr, k * 32 + fq * 8))
; #define LDB(dst, b, h) for (int n = 0; n < 2; ++n) for (int k = 0; k < 2; ++k) \
;     dst[n][k] = *reinterpret_cast<const bf16x8*>((char*)SB(b, h) + lds_byte(wc * 32 + n * 16 + fr, k * 32 + fq * 8))
; #define WAIT_V(n) asm volatile("s_waitcnt vmcnt(" #n ")" ::: "memory")
; #define WAIT_L(n) asm volatile("s_waitcnt lgkmcnt(" #n ")" ::: "memory")
; #define BAR __builtin_amdgcn_s_barrier()
; template <bool SWAP, int lda, int ldb, int K>
; __device__ __forceinline__ void gemm256(const bf16_t* __restrict__ Ap, const bf16_t* __restrict__ Bp, f32x4 (&acc)[2][2][4][2]) {
;     ...
;       BAR; WAIT_L(0); MMA(0, 0, At, B0); BAR;
;       LDB(B1, 0, 1); BAR; WAIT_L(0); MMA(0, 1, At, B1); BAR;
;       LDA(At, 0, 1); WAIT_V(4); BAR; WAIT_L(0); MMA(1, 0, At, B0); MMA(1, 1, At, B1); BAR; }
;     { LDB(B0, 1, 0); LDA(At, 1, 0); WAIT_V(2); BAR; WAIT_L(0); MMA(0, 0, At, B0); BAR;
;       LDB(B1, 1, 1); WAIT_V(0); BAR; WAIT_L(0); MMA(0, 1, At, B1); BAR;
;       LDA(At, 1, 1); BAR; WAIT_L(0); MMA(1, 0, At, B0); MMA(1, 1, At, B1); BAR; }
	s_waitcnt lgkmcnt(0)
	s_nop 0
	s_waitcnt lgkmcnt(0)
	v_mfma_f32_16x16x32_bf16 v[92:95], v[96:99], v[170:173], v[92:95]
	v_mfma_f32_16x16x32_bf16 v[84:87], v[96:99], v[178:181], v[84:87]
	v_mfma_f32_16x16x32_bf16 v[80:83], v[104:107], v[178:181], v[80:83]
	v_mfma_f32_16x16x32_bf16 v[76:79], v[96:99], v[186:189], v[76:79]
	v_mfma_f32_16x16x32_bf16 v[64:67], v[104:107], v[194:197], v[64:67]
	v_mfma_f32_16x16x32_bf16 v[92:95], v[100:103], v[174:177], v[92:95]
	v_mfma_f32_16x16x32_bf16 v[88:91], v[104:107], v[170:173], v[88:91]
	v_mfma_f32_16x16x32_bf16 v[84:87], v[100:103], v[182:185], v[84:87]
	v_mfma_f32_16x16x32_bf16 v[80:83], v[152:155], v[182:185], v[80:83]
	v_mfma_f32_16x16x32_bf16 v[76:79], v[100:103], v[190:193], v[76:79]
	v_mfma_f32_16x16x32_bf16 v[72:75], v[104:107], v[186:189], v[72:75]
	v_mfma_f32_16x16x32_bf16 v[68:71], v[96:99], v[194:197], v[68:71]
	v_mfma_f32_16x16x32_bf16 v[64:67], v[152:155], v[198:201], v[64:67]
	v_mfma_f32_16x16x32_bf16 v[170:173], v[152:155], v[174:177], v[88:91]
	v_mfma_f32_16x16x32_bf16 v[174:177], v[152:155], v[190:193], v[72:75]
	v_mfma_f32_16x16x32_bf16 v[178:181], v[100:103], v[198:201], v[68:71]
	s_nop 0
	s_barrier
	s_nop 1
	ds_read_b128 v[68:71], v140 offset:16384
	ds_read_b128 v[72:75], v140 offset:17408
	ds_read_b128 v[88:91], v139 offset:16384
	ds_read_b128 v[182:185], v139 offset:17408
	ds_read_b128 v[186:189], v138 offset:16384
	ds_read_b128 v[190:193], v138 offset:17408
	ds_read_b128 v[194:197], v137 offset:16384
	ds_read_b128 v[198:201], v137 offset:17408
	s_waitcnt vmcnt(4)
	s_barrier
	s_waitcnt lgkmcnt(0)
	s_nop 0
	s_waitcnt lgkmcnt(0)
	v_mfma_f32_16x16x32_bf16 v[52:55], v[142:145], v[88:91], v[52:55]
	v_mfma_f32_16x16x32_bf16 v[48:51], v[162:165], v[88:91], v[48:51]
	v_mfma_f32_16x16x32_bf16 v[44:47], v[142:145], v[186:189], v[44:47]
	v_mfma_f32_16x16x32_bf16 v[40:43], v[162:165], v[186:189], v[40:43]
	v_mfma_f32_16x16x32_bf16 v[36:39], v[142:145], v[194:197], v[36:39]
	v_mfma_f32_16x16x32_bf16 v[32:35], v[162:165], v[194:197], v[32:35]
	v_mfma_f32_16x16x32_bf16 v[60:63], v[142:145], v[68:71], v[60:63]
	v_mfma_f32_16x16x32_bf16 v[56:59], v[162:165], v[68:71], v[56:59]
	v_mfma_f32_16x16x32_bf16 v[52:55], v[148:151], v[182:185], v[52:55]
	v_mfma_f32_16x16x32_bf16 v[48:51], v[166:169], v[182:185], v[48:51]
	v_mfma_f32_16x16x32_bf16 v[44:47], v[148:151], v[190:193], v[44:47]
	v_mfma_f32_16x16x32_bf16 v[40:43], v[166:169], v[190:193], v[40:43]
	v_mfma_f32_16x16x32_bf16 v[36:39], v[148:151], v[198:201], v[36:39]
	v_mfma_f32_16x16x32_bf16 v[32:35], v[166:169], v[198:201], v[32:35]
	v_mfma_f32_16x16x32_bf16 v[214:217], v[148:151], v[72:75], v[60:63]
	v_mfma_f32_16x16x32_bf16 v[218:221], v[166:169], v[72:75], v[56:59]
	s_nop 0
	s_nop 0
	v_mfma_f32_16x16x32_bf16 v[28:31], v[96:99], v[68:71], v[28:31]
	v_mfma_f32_16x16x32_bf16 v[24:27], v[104:107], v[68:71], v[24:27]
	v_mfma_f32_16x16x32_bf16 v[20:23], v[96:99], v[88:91], v[20:23]
	v_mfma_f32_16x16x32_bf16 v[16:19], v[104:107], v[88:91], v[16:19]
	v_mfma_f32_16x16x32_bf16 v[12:15], v[96:99], v[186:189], v[12:15]
	v_mfma_f32_16x16x32_bf16 v[8:11], v[104:107], v[186:189], v[8:11]
	v_mfma_f32_16x16x32_bf16 v[4:7], v[96:99], v[194:197], v[4:7]
	v_mfma_f32_16x16x32_bf16 v[0:3], v[104:107], v[194:197], v[0:3]
	v_mfma_f32_16x16x32_bf16 v[28:31], v[100:103], v[72:75], v[28:31]
	v_mfma_f32_16x16x32_bf16 v[24:27], v[152:155], v[72:75], v[24:27]
	v_mfma_f32_16x16x32_bf16 v[20:23], v[100:103], v[182:185], v[20:23]
	v_mfma_f32_16x16x32_bf16 v[16:19], v[152:155], v[182:185], v[16:19]
	v_mfma_f32_16x16x32_bf16 v[12:15], v[100:103], v[190:193], v[12:15]
	v_mfma_f32_16x16x32_bf16 v[8:11], v[152:155], v[190:193], v[8:11]
	v_mfma_f32_16x16x32_bf16 v[4:7], v[100:103], v[198:201], v[4:7]
	v_mfma_f32_16x16x32_bf16 v[0:3], v[152:155], v[198:201], v[0:3]
	s_nop 0
	s_barrier
	ds_read_b128 v[142:145], v146
	ds_read_b128 v[148:151], v146 offset:1024
	ds_read_b128 v[152:155], v146 offset:2048
	ds_read_b128 v[160:163], v146 offset:3072
	ds_read_b128 v[56:59], v140 offset:32768
	ds_read_b128 v[60:63], v140 offset:33792
	ds_read_b128 v[68:71], v139 offset:32768
	ds_read_b128 v[72:75], v139 offset:33792
	ds_read_b128 v[164:167], v138 offset:32768
	ds_read_b128 v[182:185], v138 offset:33792
	ds_read_b128 v[186:189], v137 offset:32768
	ds_read_b128 v[190:193], v137 offset:33792
	s_waitcnt vmcnt(2)
	s_barrier
	s_waitcnt lgkmcnt(0)
	s_nop 0
	s_waitcnt lgkmcnt(0)
	v_mfma_f32_16x16x32_bf16 v[88:91], v[142:145], v[56:59], v[124:127]
	v_mfma_f32_16x16x32_bf16 v[124:127], v[148:151], v[60:63], v[88:91]
	v_mfma_f32_16x16x32_bf16 v[88:91], v[152:155], v[56:59], v[120:123]
	v_mfma_f32_16x16x32_bf16 v[120:123], v[160:163], v[60:63], v[88:91]
	v_mfma_f32_16x16x32_bf16 v[88:91], v[142:145], v[68:71], v[116:119]
	v_mfma_f32_16x16x32_bf16 v[116:119], v[148:151], v[72:75], v[88:91]
	v_mfma_f32_16x16x32_bf16 v[88:91], v[152:155], v[68:71], v[112:115]
	v_mfma_f32_16x16x32_bf16 v[112:115], v[160:163], v[72:75], v[88:91]
	v_mfma_f32_16x16x32_bf16 v[88:91], v[142:145], v[164:167], v[108:111]
	v_mfma_f32_16x16x32_bf16 v[104:107], v[148:151], v[182:185], v[88:91]
	v_mfma_f32_16x16x32_bf16 v[88:91], v[152:155], v[164:167], v[130:133]
	v_mfma_f32_16x16x32_bf16 v[100:103], v[160:163], v[182:185], v[88:91]
	v_mfma_f32_16x16x32_bf16 v[88:91], v[142:145], v[186:189], v[156:159]
	v_mfma_f32_16x16x32_bf16 v[96:99], v[148:151], v[190:193], v[88:91]
	v_mfma_f32_16x16x32_bf16 v[88:91], v[152:155], v[186:189], v[202:205]
	v_mfma_f32_16x16x32_bf16 v[88:91], v[160:163], v[190:193], v[88:91]
	s_nop 0
	s_barrier
	ds_read_b128 v[130:133], v141
	ds_read_b128 v[156:159], v141 offset:1024
	ds_read_b128 v[194:197], v141 offset:2048
	ds_read_b128 v[198:201], v141 offset:3072
	s_waitcnt vmcnt(0)
	s_barrier
; #define LDA(dst, b, h) for (int m = 0; m < 4; ++m) for (int k = 0; k < 2; ++k) \
;     dst[m][k] = *reinterpret_cast<const bf16x8*>((char*)SA(b, h) + lds_byte(wr * 64 + m * 16 + fr, k * 32 + fq * 8))
; #define LDB(dst, b, h) for (int n = 0; n < 2; ++n) for (int k = 0; k < 2; ++k) \
;     dst[n][k] = *reinterpret_cast<const bf16x8*>((char*)SB(b, h) + lds_byte(wc * 32 + n * 16 + fr, k * 32 + fq * 8))
; #define WAIT_V(n) asm volatile("s_waitcnt vmcnt(" #n ")" ::: "memory")
; #define WAIT_L(n) asm volatile("s_waitcnt lgkmcnt(" #n ")" ::: "memory")
; #define BAR __builtin_amdgcn_s_barrier()
; template <bool SWAP, int lda, int ldb, int K>
; __device__ __forceinline__ void gemm256(const bf16_t* __restrict__ Ap, const bf16_t* __restrict__ Bp, f32x4 (&acc)[2][2][4][2]) {
;     ...
;     { LDB(B0, 1, 0); LDA(At, 1, 0); WAIT_V(2); BAR; WAIT_L(0); MMA(0, 0, At, B0); BAR;
;       LDB(B1, 1, 1); WAIT_V(0); BAR; WAIT_L(0); MMA(0, 1, At, B1); BAR;
;       LDA(At, 1, 1); BAR; WAIT_L(0); MMA(1, 0, At, B0); MMA(1, 1, At, B1); BAR; }
;     if (wr == 0) BAR;
	s_waitcnt lgkmcnt(0)
	s_nop 0
	s_waitcnt lgkmcnt(0)
	v_mfma_f32_16x16x32_bf16 v[92:95], v[130:133], v[56:59], v[92:95]
	v_mfma_f32_16x16x32_bf16 v[56:59], v[194:197], v[56:59], v[170:173]
	v_mfma_f32_16x16x32_bf16 v[108:111], v[156:159], v[60:63], v[92:95]
	v_mfma_f32_16x16x32_bf16 v[92:95], v[198:201], v[60:63], v[56:59]
	v_mfma_f32_16x16x32_bf16 v[56:59], v[130:133], v[68:71], v[84:87]
	v_mfma_f32_16x16x32_bf16 v[84:87], v[156:159], v[72:75], v[56:59]
	v_mfma_f32_16x16x32_bf16 v[56:59], v[194:197], v[68:71], v[80:83]
	v_mfma_f32_16x16x32_bf16 v[80:83], v[198:201], v[72:75], v[56:59]
	v_mfma_f32_16x16x32_bf16 v[56:59], v[130:133], v[164:167], v[76:79]
	v_mfma_f32_16x16x32_bf16 v[72:75], v[156:159], v[182:185], v[56:59]
	v_mfma_f32_16x16x32_bf16 v[56:59], v[194:197], v[164:167], v[174:177]
	v_mfma_f32_16x16x32_bf16 v[68:71], v[198:201], v[182:185], v[56:59]
	v_mfma_f32_16x16x32_bf16 v[56:59], v[130:133], v[186:189], v[178:181]
	v_mfma_f32_16x16x32_bf16 v[60:63], v[156:159], v[190:193], v[56:59]
	v_mfma_f32_16x16x32_bf16 v[56:59], v[194:197], v[186:189], v[64:67]
	v_mfma_f32_16x16x32_bf16 v[56:59], v[198:201], v[190:193], v[56:59]
	s_nop 0
	s_barrier
	ds_read_b128 v[164:167], v140 offset:49152
	ds_read_b128 v[168:171], v140 offset:50176
	ds_read_b128 v[172:175], v139 offset:49152
	ds_read_b128 v[176:179], v139 offset:50176
	ds_read_b128 v[180:183], v138 offset:49152
	ds_read_b128 v[138:141], v138 offset:50176
	ds_read_b128 v[184:187], v137 offset:49152
	ds_read_b128 v[188:191], v137 offset:50176
	s_barrier
	s_waitcnt lgkmcnt(0)
	s_nop 0
	s_waitcnt lgkmcnt(0)
	v_mfma_f32_16x16x32_bf16 v[64:67], v[142:145], v[164:167], v[214:217]
	v_mfma_f32_16x16x32_bf16 v[76:79], v[148:151], v[168:171], v[64:67]
	v_mfma_f32_16x16x32_bf16 v[64:67], v[152:155], v[164:167], v[218:221]
	v_mfma_f32_16x16x32_bf16 v[52:55], v[142:145], v[172:175], v[52:55]
	v_mfma_f32_16x16x32_bf16 v[48:51], v[152:155], v[172:175], v[48:51]
	v_mfma_f32_16x16x32_bf16 v[44:47], v[142:145], v[180:183], v[44:47]
	v_mfma_f32_16x16x32_bf16 v[40:43], v[152:155], v[180:183], v[40:43]
	v_mfma_f32_16x16x32_bf16 v[36:39], v[142:145], v[184:187], v[36:39]
	v_mfma_f32_16x16x32_bf16 v[32:35], v[152:155], v[184:187], v[32:35]
	v_mfma_f32_16x16x32_bf16 v[64:67], v[160:163], v[168:171], v[64:67]
	v_mfma_f32_16x16x32_bf16 v[52:55], v[148:151], v[176:179], v[52:55]
	v_mfma_f32_16x16x32_bf16 v[48:51], v[160:163], v[176:179], v[48:51]
	v_mfma_f32_16x16x32_bf16 v[44:47], v[148:151], v[138:141], v[44:47]
	v_mfma_f32_16x16x32_bf16 v[40:43], v[160:163], v[138:141], v[40:43]
	v_mfma_f32_16x16x32_bf16 v[36:39], v[148:151], v[188:191], v[36:39]
	v_mfma_f32_16x16x32_bf16 v[32:35], v[160:163], v[188:191], v[32:35]
	s_nop 0
	s_nop 0
	v_mfma_f32_16x16x32_bf16 v[28:31], v[130:133], v[164:167], v[28:31]
	v_mfma_f32_16x16x32_bf16 v[24:27], v[194:197], v[164:167], v[24:27]
	v_mfma_f32_16x16x32_bf16 v[20:23], v[130:133], v[172:175], v[20:23]
	v_mfma_f32_16x16x32_bf16 v[16:19], v[194:197], v[172:175], v[16:19]
	v_mfma_f32_16x16x32_bf16 v[12:15], v[130:133], v[180:183], v[12:15]
	v_mfma_f32_16x16x32_bf16 v[8:11], v[194:197], v[180:183], v[8:11]
	v_mfma_f32_16x16x32_bf16 v[4:7], v[130:133], v[184:187], v[4:7]
	v_mfma_f32_16x16x32_bf16 v[0:3], v[194:197], v[184:187], v[0:3]
	v_mfma_f32_16x16x32_bf16 v[28:31], v[156:159], v[168:171], v[28:31]
	v_mfma_f32_16x16x32_bf16 v[24:27], v[198:201], v[168:171], v[24:27]
	v_mfma_f32_16x16x32_bf16 v[20:23], v[156:159], v[176:179], v[20:23]
	v_mfma_f32_16x16x32_bf16 v[16:19], v[198:201], v[176:179], v[16:19]
	v_mfma_f32_16x16x32_bf16 v[12:15], v[156:159], v[138:141], v[12:15]
	v_mfma_f32_16x16x32_bf16 v[8:11], v[198:201], v[138:141], v[8:11]
	v_mfma_f32_16x16x32_bf16 v[4:7], v[156:159], v[188:191], v[4:7]
	v_mfma_f32_16x16x32_bf16 v[0:3], v[198:201], v[188:191], v[0:3]
	s_nop 0
	v_cmp_gt_u32_e32 vcc, s91, v136
	s_barrier
	s_and_saveexec_b64 s[0:1], vcc
	s_cbranch_execz .LBB0_380
	s_barrier
; __device__ __forceinline__ float sigmoidf_(float x) { return __builtin_amdgcn_rcpf(1.0f + __expf(-x)); }
; __device__ __forceinline__ int tid_opaque() { int t = threadIdx.x; asm volatile("" : "+v"(t)); return t; }
; template <int ACT>
; __device__ __forceinline__ void epi_stage(f32x4 (&acc)[2][2][4][2]) {
;     const int et = tid_opaque();
;     const int wr = (et >> 8) & 1, wc = (et >> 6) & 3, fr = et & 15, fq = (et >> 4) & 3;
;     char* lds = (char*)shm;
; #pragma unroll
;     for (int ai = 0; ai < 2; ++ai)
; #pragma unroll
;         for (int bj = 0; bj < 2; ++bj)
; #pragma unroll
;             for (int m = 0; m < 4; ++m)
; #pragma unroll
;                 for (int n = 0; n < 2; ++n) {
;                     const int row = ai * 128 + wr * 64 + m * 16 + fr;
;                     const int c8 = ((bj * 128 + wc * 32 + n * 16) >> 2) + fq;
;                     f32x4 a = acc[ai][bj][m][n];
;                     if (ACT == 1) {
; #pragma unroll
;                         for (int j = 0; j < 4; ++j) a[j] = a[j] * sigmoidf_(a[j]);
;                     }
;                     if (ACT == 2) {
; #pragma unroll
;                         for (int j = 0; j < 4; ++j) a[j] = sigmoidf_(a[j]);
;                     }
;                     uint2 o; o.x = pk2(a[0], a[1]); o.y = pk2(a[2], a[3]);
;                     *reinterpret_cast<uint2*>(lds + row * 512 + ((c8 ^ fr) << 3)) = o;
;                 }
;     __syncthreads();
.LBB0_380:
	s_or_b64 exec, exec, s[0:1]
	s_setprio 0
	v_mov_b32_e32 v128, v208
	v_cvt_pk_bf16_f32 v124, v124, v125
	v_and_b32_e32 v130, 15, v128
	v_bfe_u32 v131, v128, 4, 2
	v_lshrrev_b32_e32 v132, 2, v128
	v_lshrrev_b32_e32 v128, 3, v128
	v_and_b32_e32 v128, 24, v128
	v_and_or_b32 v132, v132, 64, v130
	v_lshlrev_b32_e32 v132, 9, v132
	v_cvt_pk_bf16_f32 v125, v126, v127
	v_bitop3_b32 v126, v128, v130, v131 bitop3:0x36
	v_or_b32_e32 v133, v128, v131
	v_add_u32_e32 v134, 0, v132
	v_lshlrev_b32_e32 v126, 3, v126
	v_add_u32_e32 v127, v134, v126
	v_cvt_pk_bf16_f32 v104, v104, v105
	v_cvt_pk_bf16_f32 v105, v106, v107
	v_cvt_pk_bf16_f32 v96, v96, v97
	v_cvt_pk_bf16_f32 v97, v98, v99
	v_cvt_pk_bf16_f32 v88, v88, v89
	v_cvt_pk_bf16_f32 v89, v90, v91
	v_bitop3_b32 v90, v133, v130, 32 bitop3:0x36
	s_waitcnt vmcnt(0)
	ds_write2st64_b64 v127, v[104:105], v[96:97] offset0:32 offset1:48
	v_lshlrev_b32_e32 v96, 3, v90
	v_cvt_pk_bf16_f32 v90, v92, v93
	v_bitop3_b32 v92, v133, v130, 36 bitop3:0x36
	v_lshlrev_b32_e32 v92, 3, v92
	v_cvt_pk_bf16_f32 v56, v56, v57
	v_cvt_pk_bf16_f32 v57, v58, v59
	v_or_b32_e32 v58, 0x10000, v132
	v_cvt_pk_bf16_f32 v120, v120, v121
	v_cvt_pk_bf16_f32 v121, v122, v123
	v_bitop3_b32 v122, v133, v130, 4 bitop3:0x36
	v_add_u32_e32 v97, v134, v96
	v_add_u32_e32 v93, v134, v92
	v_cvt_pk_bf16_f32 v72, v72, v73
	v_cvt_pk_bf16_f32 v73, v74, v75
	v_cvt_pk_bf16_f32 v68, v68, v69
	v_cvt_pk_bf16_f32 v69, v70, v71
	v_cvt_pk_bf16_f32 v60, v60, v61
	v_cvt_pk_bf16_f32 v61, v62, v63
	v_add_u32_e32 v59, 0, v58
	v_lshlrev_b32_e32 v122, 3, v122
	ds_write2st64_b64 v97, v[72:73], v[60:61] offset0:32 offset1:48
	ds_write2st64_b64 v93, v[68:69], v[56:57] offset0:32 offset1:48
	v_cvt_pk_bf16_f32 v56, v76, v77
	v_cvt_pk_bf16_f32 v57, v78, v79
	v_add_u32_e32 v60, v59, v126
	ds_write_b64 v60, v[56:57]
	v_cvt_pk_bf16_f32 v56, v64, v65
	v_cvt_pk_bf16_f32 v57, v66, v67
	v_add_u32_e32 v60, v59, v122
	s_add_i32 s0, 0, 0x2000
	ds_write_b64 v60, v[56:57]
	v_add_u32_e32 v56, s0, v58
	v_cvt_pk_bf16_f32 v48, v48, v49
	v_cvt_pk_bf16_f32 v49, v50, v51
	v_add_u32_e32 v50, v56, v122
	s_add_i32 s0, 0, 0x4000
	ds_write_b64 v50, v[48:49]
	v_add_u32_e32 v48, s0, v58
	v_cvt_pk_bf16_f32 v40, v40, v41
	v_cvt_pk_bf16_f32 v41, v42, v43
	v_add_u32_e32 v42, v48, v122
	s_add_i32 s0, 0, 0x6000
	ds_write_b64 v42, v[40:41]
	v_add_u32_e32 v40, s0, v58
	v_add_u32_e32 v123, v134, v122
	v_cvt_pk_bf16_f32 v100, v100, v101
	v_cvt_pk_bf16_f32 v101, v102, v103
	v_cvt_pk_bf16_f32 v0, v0, v1
	v_cvt_pk_bf16_f32 v1, v2, v3
	v_add_u32_e32 v2, v40, v92
	v_cvt_pk_bf16_f32 v116, v116, v117
	v_cvt_pk_bf16_f32 v117, v118, v119
	v_cvt_pk_bf16_f32 v112, v112, v113
	v_cvt_pk_bf16_f32 v113, v114, v115
	ds_write2st64_b64 v123, v[100:101], v[88:89] offset0:32 offset1:48
	v_cvt_pk_bf16_f32 v88, v108, v109
	v_cvt_pk_bf16_f32 v89, v110, v111
	v_cvt_pk_bf16_f32 v91, v94, v95
	v_cvt_pk_bf16_f32 v84, v84, v85
	v_cvt_pk_bf16_f32 v85, v86, v87
	v_cvt_pk_bf16_f32 v80, v80, v81
	v_cvt_pk_bf16_f32 v81, v82, v83
	v_cvt_pk_bf16_f32 v52, v52, v53
	v_cvt_pk_bf16_f32 v53, v54, v55
	v_add_u32_e32 v54, v56, v126
	v_cvt_pk_bf16_f32 v44, v44, v45
	v_cvt_pk_bf16_f32 v45, v46, v47
	v_add_u32_e32 v46, v48, v126
	v_cvt_pk_bf16_f32 v36, v36, v37
	v_cvt_pk_bf16_f32 v37, v38, v39
	v_add_u32_e32 v38, v40, v126
	v_cvt_pk_bf16_f32 v32, v32, v33
	v_cvt_pk_bf16_f32 v33, v34, v35
	v_add_u32_e32 v34, v40, v122
	v_cvt_pk_bf16_f32 v28, v28, v29
	v_cvt_pk_bf16_f32 v29, v30, v31
	v_add_u32_e32 v30, v59, v96
	v_cvt_pk_bf16_f32 v24, v24, v25
	v_cvt_pk_bf16_f32 v25, v26, v27
	v_add_u32_e32 v26, v59, v92
	v_cvt_pk_bf16_f32 v20, v20, v21
	v_cvt_pk_bf16_f32 v21, v22, v23
	v_add_u32_e32 v22, v56, v96
	v_cvt_pk_bf16_f32 v16, v16, v17
	v_cvt_pk_bf16_f32 v17, v18, v19
	v_add_u32_e32 v18, v56, v92
	v_cvt_pk_bf16_f32 v12, v12, v13
	v_cvt_pk_bf16_f32 v13, v14, v15
	v_add_u32_e32 v14, v48, v96
	v_cvt_pk_bf16_f32 v8, v8, v9
	v_cvt_pk_bf16_f32 v9, v10, v11
	v_add_u32_e32 v10, v48, v92
	v_cvt_pk_bf16_f32 v4, v4, v5
	v_cvt_pk_bf16_f32 v5, v6, v7
	v_add_u32_e32 v6, v40, v96
	ds_write_b64 v2, v[0:1]
	v_mov_b32_e32 v0, v208
	ds_write2st64_b64 v127, v[124:125], v[116:117] offset1:16
	ds_write2st64_b64 v123, v[120:121], v[112:113] offset1:16
	ds_write2st64_b64 v97, v[88:89], v[84:85] offset1:16
	ds_write2st64_b64 v93, v[90:91], v[80:81] offset1:16
	ds_write_b64 v54, v[52:53]
	ds_write_b64 v46, v[44:45]
	ds_write_b64 v38, v[36:37]
	ds_write_b64 v34, v[32:33]
	ds_write_b64 v30, v[28:29]
	ds_write_b64 v26, v[24:25]
	ds_write_b64 v22, v[20:21]
	ds_write_b64 v18, v[16:17]
	ds_write_b64 v14, v[12:13]
	ds_write_b64 v10, v[8:9]
	ds_write_b64 v6, v[4:5]
	s_waitcnt lgkmcnt(0)
	s_barrier
	s_add_u32 s2, s23, s18
	v_ashrrev_i32_e32 v63, 5, v0
	v_and_b32_e32 v62, 31, v0
	s_addc_u32 s3, s24, 0
	v_mul_lo_u32 v1, v63, s55
	v_and_b32_e32 v0, 32, v0
	v_lshlrev_b32_e32 v2, 4, v62
	s_cmp_lg_u32 s26, 2
	v_cmp_eq_u32_e64 s[4:5], 0, v0
	v_lshl_or_b32 v0, v62, 3, v1
	v_lshl_or_b32 v128, v63, 11, v2
	s_cselect_b64 s[16:17], -1, 0
	v_add_u32_e32 v64, 0x54000, v0
	v_lshl_add_u32 v65, v63, 9, 0
	s_mov_b64 s[18:19], -1
	s_branch .LBB0_382

; __device__ __forceinline__ int tid_opaque() { int t = threadIdx.x; asm volatile("" : "+v"(t)); return t; }
; #define BAR __builtin_amdgcn_s_barrier()
; template <bool SWAP, int lda, int ldb, int K>
; __device__ __forceinline__ void gemm256(const bf16_t* __restrict__ Ap, const bf16_t* __restrict__ Bp, f32x4 (&acc)[2][2][4][2]) {
;     ...
;     const int gtid = tid_opaque();
;     const int wid = gtid >> 6, lane = gtid & 63, wr = wid >> 2, wc = wid & 3, fr = lane & 15, fq = lane >> 4;
;     bf16x8 At[4][2], B0[2][2], B1[2][2];
;     constexpr int nt = K / BK;
;     unsigned offA[2], offB[2];
;     for (int _i = 0; _i < 2; ++_i) {
;         int _b = gtid * 16 + _i * 8192; int _r, _c; stage_rc(_b, _r, _c);
;         offA[_i] = (unsigned)(_r * lda + _c) * 2u; offB[_i] = (unsigned)(_r * ldb + _c) * 2u;
;     }
;     STAGE(SB(0, 0), Bp, ldb, 0, 0); STAGE(SA(0, 0), Ap, lda, 0, 0);
;     STAGE(SB(0, 1), Bp, ldb, HALF, 0); STAGE(SA(0, 1), Ap, lda, HALF, 0);
;     if (wr == 1) BAR;
; __device__ __forceinline__ void phase_D(const Params& p, int l) {
;     ...
;     for (int t = blockIdx.x; t < 64 * 4; t += gridDim.x) {
;         int pm, pn; tile_map(t, 4, pm, pn);
;         const int brow = pm * 256, bcol = pn * 256;
;         f32x4 acc[2][2][4][2];
;         zero_acc(acc);
;         gemm256<true, 1024, 1024, 1024>((const bf16_t*)(p.ws + WS_H) + (long)brow * 1024, WO + (long)bcol * 1024, acc);
.LBB0_457:
	v_mov_b32_e32 v132, v208
	s_lshl_b32 s1, s14, 5
	v_bfe_i32 v2, v132, 27, 1
	v_lshlrev_b32_e32 v0, 4, v132
	v_lshrrev_b32_e32 v2, 22, v2
	v_add_u32_e32 v2, v0, v2
	v_and_b32_e32 v2, 0xfffffc00, v2
	v_sub_u32_e32 v2, v0, v2
	v_lshrrev_b32_e32 v3, 4, v2
	v_bitop3_b32 v3, v3, v2, 32 bitop3:0x6c
	v_ashrrev_i32_e32 v2, 31, v2
	v_ashrrev_i32_e32 v1, 31, v132
	v_lshrrev_b32_e32 v2, 26, v2
	v_lshrrev_b32_e32 v1, 26, v1
	v_add_u32_e32 v2, v3, v2
	v_add_u32_e32 v1, v132, v1
	v_ashrrev_i32_e32 v2, 6, v2
	v_ashrrev_i32_e32 v1, 6, v1
	v_mul_i32_i24_e32 v5, 64, v2
	v_lshlrev_b32_e32 v4, 3, v1
	v_lshlrev_b32_e32 v1, 5, v1
	v_sub_u32_e32 v3, v3, v5
	v_and_b32_e32 v4, 0x1ffff0, v4
	v_and_b32_e32 v1, 32, v1
	v_ashrrev_i16_sdwa v3, v210, sext(v3) dst_sel:DWORD dst_unused:UNUSED_PAD src0_sel:DWORD src1_sel:BYTE_0
	s_ashr_i32 s0, s14, 3
	s_and_b32 s1, s1, 0xe0
	v_add_u32_sdwa v1, v1, sext(v3) dst_sel:DWORD dst_unused:UNUSED_PAD src0_sel:DWORD src1_sel:WORD_0
	v_add_lshl_u32 v2, v2, v4, 11
	s_add_i32 s0, s1, s0
	v_lshl_add_u32 v128, v1, 1, v2
	v_add_u32_e32 v1, 0x2000, v0
	s_ashr_i32 s1, s0, 31
	v_ashrrev_i32_e32 v2, 31, v1
	s_lshr_b32 s1, s1, 27
	v_lshrrev_b32_e32 v2, 22, v2
	s_add_i32 s1, s0, s1
	v_add_u32_e32 v2, v1, v2
	s_and_b32 s2, s1, 0xffffffe0
	v_ashrrev_i32_e32 v2, 10, v2
	s_sub_i32 s0, s0, s2
	v_mul_i32_i24_e32 v3, 0x400, v2
	s_ashr_i32 s15, s0, 3
	s_lshl_b32 s1, s1, 6
	s_lshl_b32 s0, s0, 8
	v_sub_u32_e32 v1, v1, v3
	s_and_b32 s16, s1, 0xfffff800
	s_and_b32 s17, s0, 0x700
	v_lshrrev_b32_e32 v3, 4, v1
	s_or_b32 s6, s17, s16
	v_bitop3_b32 v1, v3, v1, 32 bitop3:0x6c
	s_ashr_i32 s7, s6, 31
	v_ashrrev_i32_e32 v4, 31, v1
	s_lshl_b32 s4, s15, 8
	s_lshl_b64 s[0:1], s[6:7], 11
	v_lshrrev_b32_e32 v4, 26, v4
	s_add_u32 s2, s74, s0
	v_add_u32_e32 v4, v1, v4
	s_addc_u32 s3, s75, s1
	s_ashr_i32 s5, s4, 31
	v_lshrrev_b32_e32 v5, 6, v4
	v_and_b32_e32 v4, 0xc0, v4
	s_lshl_b64 s[0:1], s[4:5], 11
	v_lshlrev_b32_e32 v3, 3, v2
	v_lshlrev_b32_e32 v2, 5, v2
	v_sub_u32_e32 v1, v1, v4
	v_add_u32_e32 v138, s90, v0
	s_add_u32 s8, s84, s0
	v_and_b32_e32 v3, 0x1ffff0, v3
	v_and_b32_e32 v2, 32, v2
	v_ashrrev_i16_sdwa v1, v210, sext(v1) dst_sel:DWORD dst_unused:UNUSED_PAD src0_sel:DWORD src1_sel:BYTE_0
	v_readfirstlane_b32 s0, v138
	v_add_u32_e32 v139, 0x2000, v138
	s_addc_u32 s9, s85, s1
	v_add_u32_sdwa v1, v2, sext(v1) dst_sel:DWORD dst_unused:UNUSED_PAD src0_sel:DWORD src1_sel:WORD_0
	v_add_lshl_u32 v2, v5, v3, 11
	s_mov_b32 m0, s0
	v_readfirstlane_b32 s0, v139
	v_add_u32_e32 v140, 0, v0
	v_lshl_add_u32 v130, v1, 1, v2
	global_load_lds_dwordx4 v128, s[8:9]
	s_mov_b32 m0, s0
	v_readfirstlane_b32 s0, v140
	v_add_u32_e32 v141, 0x2000, v140
	global_load_lds_dwordx4 v130, s[8:9]
	s_mov_b32 m0, s0
	v_readfirstlane_b32 s0, v141
	v_add_u32_e32 v143, s64, v0
	global_load_lds_dwordx4 v128, s[2:3]
	s_mov_b32 m0, s0
	s_add_u32 s10, s8, 0x40000
	v_readfirstlane_b32 s0, v143
	v_add_u32_e32 v144, 0x2000, v143
	global_load_lds_dwordx4 v130, s[2:3]
	s_addc_u32 s11, s9, 0
	s_mov_b32 m0, s0
	v_readfirstlane_b32 s0, v144
	v_add_u32_e32 v145, 0x4000, v140
	global_load_lds_dwordx4 v128, s[10:11]
	s_mov_b32 m0, s0
	s_add_u32 s0, s2, 0x40000
	v_readfirstlane_b32 s12, v145
	v_add_u32_e32 v146, 0x6000, v140
	global_load_lds_dwordx4 v130, s[10:11]
	s_addc_u32 s1, s3, 0
	s_mov_b32 m0, s12
	v_readfirstlane_b32 s12, v146
	global_load_lds_dwordx4 v128, s[0:1]
	s_mov_b32 m0, s12
	v_ashrrev_i32_e32 v1, 8, v132
	global_load_lds_dwordx4 v130, s[0:1]
	v_cmp_eq_u32_e32 vcc, 1, v1
	s_and_saveexec_b64 s[12:13], vcc
	s_cbranch_execz .LBB0_459
	s_barrier
	s_setprio 1

; #define LDA(dst, b, h) for (int m = 0; m < 4; ++m) for (int k = 0; k < 2; ++k) \
;     dst[m][k] = *reinterpret_cast<const bf16x8*>((char*)SA(b, h) + lds_byte(wr * 64 + m * 16 + fr, k * 32 + fq * 8))
; #define LDB(dst, b, h) for (int n = 0; n < 2; ++n) for (int k = 0; k < 2; ++k) \
;     dst[n][k] = *reinterpret_cast<const bf16x8*>((char*)SB(b, h) + lds_byte(wc * 32 + n * 16 + fr, k * 32 + fq * 8))
; #define WAIT_V(n) asm volatile("s_waitcnt vmcnt(" #n ")" ::: "memory")
; #define WAIT_L(n) asm volatile("s_waitcnt lgkmcnt(" #n ")" ::: "memory")
; #define BAR __builtin_amdgcn_s_barrier()
; #define SCHED __builtin_amdgcn_sched_barrier(0)
; template <bool SWAP, int lda, int ldb, int K>
; __device__ __forceinline__ void gemm256(const bf16_t* __restrict__ Ap, const bf16_t* __restrict__ Bp, f32x4 (&acc)[2][2][4][2]) {
;     ...
;     for (int t = 0; t < nt - 2; t += 2) {
;         LDB(B0, 0, 0); SCHED; LDA(At, 0, 0); STAGE(SA(1, 1), Ap, lda, HALF, t + 1);
;         WAIT_L(8); BAR; WAIT_L(0); MMA(0, 0, At, B0); BAR; SCHED;
;         LDB(B1, 0, 1); STAGE(SB(0, 0), Bp, ldb, 0, t + 2);
;         BAR; WAIT_L(0); MMA(0, 1, At, B1); BAR;
;         LDA(At, 0, 1); STAGE(SA(0, 0), Ap, lda, 0, t + 2);
;         BAR; WAIT_L(0); MMA(1, 0, At, B0); BAR; SCHED;
;         STAGE(SB(0, 1), Bp, ldb, HALF, t + 2);
;         WAIT_V(6); BAR; MMA(1, 1, At, B1); BAR;
.LBB0_460:
	ds_read_b128 v[158:161], v154
	ds_read_b128 v[162:165], v154 offset:1024
	ds_read_b128 v[166:169], v154 offset:2048
	ds_read_b128 v[170:173], v154 offset:3072
	s_add_u32 s19, s16, s0
	s_addc_u32 s21, s17, s1
	s_add_u32 s20, s19, 0x80
	v_add_u32_e32 v155, 0xc000, v140
	s_addc_u32 s21, s21, 0
	v_readfirstlane_b32 s19, v155
	v_lshl_add_u64 v[156:157], s[20:21], 0, v[128:129]
	s_mov_b32 m0, s19
	ds_read_b128 v[174:177], v136
	ds_read_b128 v[178:181], v136 offset:1024
	ds_read_b128 v[182:185], v135
	ds_read_b128 v[186:189], v135 offset:1024
	ds_read_b128 v[190:193], v134
	ds_read_b128 v[194:197], v134 offset:1024
	ds_read_b128 v[198:201], v133
	ds_read_b128 v[202:205], v133 offset:1024
	global_load_lds_dwordx4 v[156:157], off
	v_add_u32_e32 v156, 0xe000, v140
	v_lshl_add_u64 v[206:207], s[20:21], 0, v[130:131]
	v_readfirstlane_b32 s19, v156
	s_mov_b32 m0, s19
	s_nop 0
	global_load_lds_dwordx4 v[206:207], off
	s_waitcnt lgkmcnt(8)
	s_barrier
	s_waitcnt lgkmcnt(0)
	s_nop 0
	s_waitcnt lgkmcnt(0)
	v_mfma_f32_16x16x32_bf16 v[124:127], v[158:161], v[174:177], v[124:127]
	v_mfma_f32_16x16x32_bf16 v[120:123], v[166:169], v[174:177], v[120:123]
	v_mfma_f32_16x16x32_bf16 v[116:119], v[158:161], v[182:185], v[116:119]
	v_mfma_f32_16x16x32_bf16 v[112:115], v[166:169], v[182:185], v[112:115]
	v_mfma_f32_16x16x32_bf16 v[108:111], v[158:161], v[190:193], v[108:111]
	v_mfma_f32_16x16x32_bf16 v[104:107], v[166:169], v[190:193], v[104:107]
	v_mfma_f32_16x16x32_bf16 v[100:103], v[158:161], v[198:201], v[100:103]
	v_mfma_f32_16x16x32_bf16 v[96:99], v[166:169], v[198:201], v[96:99]
	v_mfma_f32_16x16x32_bf16 v[124:127], v[162:165], v[178:181], v[124:127]
	v_mfma_f32_16x16x32_bf16 v[120:123], v[170:173], v[178:181], v[120:123]
	v_mfma_f32_16x16x32_bf16 v[116:119], v[162:165], v[186:189], v[116:119]
	v_mfma_f32_16x16x32_bf16 v[112:115], v[170:173], v[186:189], v[112:115]
	v_mfma_f32_16x16x32_bf16 v[108:111], v[162:165], v[194:197], v[108:111]
	v_mfma_f32_16x16x32_bf16 v[104:107], v[170:173], v[194:197], v[104:107]
	v_mfma_f32_16x16x32_bf16 v[100:103], v[162:165], v[202:205], v[100:103]
	v_mfma_f32_16x16x32_bf16 v[96:99], v[170:173], v[202:205], v[96:99]
	s_nop 0
	s_barrier
	s_add_u32 s19, s8, s0
	s_addc_u32 s22, s9, s1
	s_add_u32 s20, s19, 0x100
	s_addc_u32 s21, s22, 0
	v_readfirstlane_b32 s23, v138
	v_lshl_add_u64 v[206:207], s[20:21], 0, v[128:129]
	s_mov_b32 m0, s23
	ds_read_b128 v[214:217], v151
	ds_read_b128 v[218:221], v151 offset:1024
	ds_read_b128 v[222:225], v151 offset:2048
	ds_read_b128 v[226:229], v151 offset:3072
	global_load_lds_dwordx4 v[206:207], off
	v_lshl_add_u64 v[206:207], s[20:21], 0, v[130:131]
	v_readfirstlane_b32 s20, v139
	s_mov_b32 m0, s20
	s_nop 0
	global_load_lds_dwordx4 v[206:207], off
	s_barrier
	s_waitcnt lgkmcnt(0)
	s_nop 0
	s_waitcnt lgkmcnt(0)
	v_mfma_f32_16x16x32_bf16 v[92:95], v[214:217], v[174:177], v[92:95]
	v_mfma_f32_16x16x32_bf16 v[88:91], v[222:225], v[174:177], v[88:91]
	v_mfma_f32_16x16x32_bf16 v[84:87], v[214:217], v[182:185], v[84:87]
	v_mfma_f32_16x16x32_bf16 v[80:83], v[222:225], v[182:185], v[80:83]
	v_mfma_f32_16x16x32_bf16 v[76:79], v[214:217], v[190:193], v[76:79]
	v_mfma_f32_16x16x32_bf16 v[72:75], v[222:225], v[190:193], v[72:75]
	v_mfma_f32_16x16x32_bf16 v[68:71], v[214:217], v[198:201], v[68:71]
	v_mfma_f32_16x16x32_bf16 v[64:67], v[222:225], v[198:201], v[64:67]
	v_mfma_f32_16x16x32_bf16 v[92:95], v[218:221], v[178:181], v[92:95]
	v_mfma_f32_16x16x32_bf16 v[88:91], v[226:229], v[178:181], v[88:91]
	v_mfma_f32_16x16x32_bf16 v[84:87], v[218:221], v[186:189], v[84:87]
	v_mfma_f32_16x16x32_bf16 v[80:83], v[226:229], v[186:189], v[80:83]
	v_mfma_f32_16x16x32_bf16 v[76:79], v[218:221], v[194:197], v[76:79]
	v_mfma_f32_16x16x32_bf16 v[72:75], v[226:229], v[194:197], v[72:75]
	v_mfma_f32_16x16x32_bf16 v[68:71], v[218:221], v[202:205], v[68:71]
	v_mfma_f32_16x16x32_bf16 v[64:67], v[226:229], v[202:205], v[64:67]
	s_nop 0
	s_add_u32 s23, s2, s0
	s_addc_u32 s24, s3, s1
	s_add_u32 s20, s23, 0x100
	s_addc_u32 s21, s24, 0
	v_readfirstlane_b32 s25, v140
	v_lshl_add_u64 v[206:207], s[20:21], 0, v[128:129]
	s_mov_b32 m0, s25
	s_barrier
	ds_read_b128 v[174:177], v136 offset:16384
	ds_read_b128 v[178:181], v136 offset:17408
	ds_read_b128 v[182:185], v135 offset:16384
	ds_read_b128 v[186:189], v135 offset:17408
	ds_read_b128 v[190:193], v134 offset:16384
	ds_read_b128 v[194:197], v134 offset:17408
	ds_read_b128 v[198:201], v133 offset:16384
	ds_read_b128 v[202:205], v133 offset:17408
	global_load_lds_dwordx4 v[206:207], off
	v_lshl_add_u64 v[206:207], s[20:21], 0, v[130:131]
	v_readfirstlane_b32 s20, v141
	s_mov_b32 m0, s20
	s_nop 0
	global_load_lds_dwordx4 v[206:207], off
	s_barrier
	s_waitcnt lgkmcnt(0)
	s_nop 0
	s_waitcnt lgkmcnt(0)
	v_mfma_f32_16x16x32_bf16 v[60:63], v[158:161], v[174:177], v[60:63]
	v_mfma_f32_16x16x32_bf16 v[56:59], v[166:169], v[174:177], v[56:59]
	v_mfma_f32_16x16x32_bf16 v[52:55], v[158:161], v[182:185], v[52:55]
	v_mfma_f32_16x16x32_bf16 v[48:51], v[166:169], v[182:185], v[48:51]
	v_mfma_f32_16x16x32_bf16 v[44:47], v[158:161], v[190:193], v[44:47]
	v_mfma_f32_16x16x32_bf16 v[40:43], v[166:169], v[190:193], v[40:43]
	v_mfma_f32_16x16x32_bf16 v[36:39], v[158:161], v[198:201], v[36:39]
	v_mfma_f32_16x16x32_bf16 v[32:35], v[166:169], v[198:201], v[32:35]
	v_mfma_f32_16x16x32_bf16 v[60:63], v[162:165], v[178:181], v[60:63]
	v_mfma_f32_16x16x32_bf16 v[56:59], v[170:173], v[178:181], v[56:59]
	v_mfma_f32_16x16x32_bf16 v[52:55], v[162:165], v[186:189], v[52:55]
	v_mfma_f32_16x16x32_bf16 v[48:51], v[170:173], v[186:189], v[48:51]
	v_mfma_f32_16x16x32_bf16 v[44:47], v[162:165], v[194:197], v[44:47]
	v_mfma_f32_16x16x32_bf16 v[40:43], v[170:173], v[194:197], v[40:43]
	v_mfma_f32_16x16x32_bf16 v[36:39], v[162:165], v[202:205], v[36:39]
	v_mfma_f32_16x16x32_bf16 v[32:35], v[170:173], v[202:205], v[32:35]
	s_nop 0
	s_barrier
; #define LDA(dst, b, h) for (int m = 0; m < 4; ++m) for (int k = 0; k < 2; ++k) \
;     dst[m][k] = *reinterpret_cast<const bf16x8*>((char*)SA(b, h) + lds_byte(wr * 64 + m * 16 + fr, k * 32 + fq * 8))
; #define LDB(dst, b, h) for (int n = 0; n < 2; ++n) for (int k = 0; k < 2; ++k) \
;     dst[n][k] = *reinterpret_cast<const bf16x8*>((char*)SB(b, h) + lds_byte(wc * 32 + n * 16 + fr, k * 32 + fq * 8))
; #define WAIT_V(n) asm volatile("s_waitcnt vmcnt(" #n ")" ::: "memory")
; #define WAIT_L(n) asm volatile("s_waitcnt lgkmcnt(" #n ")" ::: "memory")
; #define BAR __builtin_amdgcn_s_barrier()
; #define SCHED __builtin_amdgcn_sched_barrier(0)
; template <bool SWAP, int lda, int ldb, int K>
; __device__ __forceinline__ void gemm256(const bf16_t* __restrict__ Ap, const bf16_t* __restrict__ Bp, f32x4 (&acc)[2][2][4][2]) {
;     ...
;         LDB(B0, 0, 0); SCHED; LDA(At, 0, 0); STAGE(SA(1, 1), Ap, lda, HALF, t + 1);
;         WAIT_L(8); BAR; WAIT_L(0); MMA(0, 0, At, B0); BAR; SCHED;
;         LDB(B1, 0, 1); STAGE(SB(0, 0), Bp, ldb, 0, t + 2);
;         BAR; WAIT_L(0); MMA(0, 1, At, B1); BAR;
;         LDA(At, 0, 1); STAGE(SA(0, 0), Ap, lda, 0, t + 2);
;         BAR; WAIT_L(0); MMA(1, 0, At, B0); BAR; SCHED;
;         STAGE(SB(0, 1), Bp, ldb, HALF, t + 2);
;         WAIT_V(6); BAR; MMA(1, 1, At, B1); BAR;
;         LDB(B0, 1, 0); SCHED; LDA(At, 1, 0); STAGE(SA(0, 1), Ap, lda, HALF, t + 2);
;         WAIT_L(8); BAR; WAIT_L(0); MMA(0, 0, At, B0); BAR; SCHED;
;         LDB(B1, 1, 1); STAGE(SB(1, 0), Bp, ldb, 0, t + 3);
;         BAR; WAIT_L(0); MMA(0, 1, At, B1); BAR;
;         LDA(At, 1, 1); STAGE(SA(1, 0), Ap, lda, 0, t + 3);
;         BAR; WAIT_L(0); MMA(1, 0, At, B0); BAR; SCHED;
;         STAGE(SB(1, 1), Bp, ldb, HALF, t + 3);
;         WAIT_V(6); BAR; MMA(1, 1, At, B1); BAR;
	s_add_u32 s25, s10, s0
	s_addc_u32 s26, s11, s1
	s_add_u32 s20, s25, 0x100
	s_addc_u32 s21, s26, 0
	v_readfirstlane_b32 s27, v143
	v_lshl_add_u64 v[158:159], s[20:21], 0, v[128:129]
	s_mov_b32 m0, s27
	s_nop 0
	global_load_lds_dwordx4 v[158:159], off
	v_lshl_add_u64 v[158:159], s[20:21], 0, v[130:131]
	v_readfirstlane_b32 s20, v144
	s_mov_b32 m0, s20
	s_nop 0
	global_load_lds_dwordx4 v[158:159], off
	s_waitcnt vmcnt(6)
	s_barrier
	s_nop 0
	v_mfma_f32_16x16x32_bf16 v[28:31], v[214:217], v[174:177], v[28:31]
	v_mfma_f32_16x16x32_bf16 v[24:27], v[222:225], v[174:177], v[24:27]
	v_mfma_f32_16x16x32_bf16 v[20:23], v[214:217], v[182:185], v[20:23]
	v_mfma_f32_16x16x32_bf16 v[16:19], v[222:225], v[182:185], v[16:19]
	v_mfma_f32_16x16x32_bf16 v[12:15], v[214:217], v[190:193], v[12:15]
	v_mfma_f32_16x16x32_bf16 v[8:11], v[222:225], v[190:193], v[8:11]
	v_mfma_f32_16x16x32_bf16 v[4:7], v[214:217], v[198:201], v[4:7]
	v_mfma_f32_16x16x32_bf16 v[0:3], v[222:225], v[198:201], v[0:3]
	v_mfma_f32_16x16x32_bf16 v[28:31], v[218:221], v[178:181], v[28:31]
	v_mfma_f32_16x16x32_bf16 v[24:27], v[226:229], v[178:181], v[24:27]
	v_mfma_f32_16x16x32_bf16 v[20:23], v[218:221], v[186:189], v[20:23]
	v_mfma_f32_16x16x32_bf16 v[16:19], v[226:229], v[186:189], v[16:19]
	v_mfma_f32_16x16x32_bf16 v[12:15], v[218:221], v[194:197], v[12:15]
	v_mfma_f32_16x16x32_bf16 v[8:11], v[226:229], v[194:197], v[8:11]
	v_mfma_f32_16x16x32_bf16 v[4:7], v[218:221], v[202:205], v[4:7]
	v_mfma_f32_16x16x32_bf16 v[0:3], v[226:229], v[202:205], v[0:3]
	s_nop 0
	s_barrier
	ds_read_b128 v[158:161], v142
	ds_read_b128 v[162:165], v142 offset:1024
	ds_read_b128 v[166:169], v142 offset:2048
	ds_read_b128 v[170:173], v142 offset:3072
	s_add_u32 s20, s12, s0
	s_addc_u32 s21, s13, s1
	v_readfirstlane_b32 s27, v145
	v_lshl_add_u64 v[206:207], s[20:21], 0, v[128:129]
	s_mov_b32 m0, s27
	ds_read_b128 v[174:177], v136 offset:32768
	ds_read_b128 v[178:181], v136 offset:33792
	ds_read_b128 v[182:185], v135 offset:32768
	ds_read_b128 v[186:189], v135 offset:33792
	ds_read_b128 v[190:193], v134 offset:32768
	ds_read_b128 v[194:197], v134 offset:33792
	ds_read_b128 v[198:201], v133 offset:32768
	ds_read_b128 v[202:205], v133 offset:33792
	global_load_lds_dwordx4 v[206:207], off
	v_lshl_add_u64 v[206:207], s[20:21], 0, v[130:131]
	v_readfirstlane_b32 s20, v146
	s_mov_b32 m0, s20
	s_nop 0
	global_load_lds_dwordx4 v[206:207], off
	s_waitcnt lgkmcnt(8)
	s_barrier
	s_waitcnt lgkmcnt(0)
	s_nop 0
	s_waitcnt lgkmcnt(0)
	v_mfma_f32_16x16x32_bf16 v[124:127], v[158:161], v[174:177], v[124:127]
	v_mfma_f32_16x16x32_bf16 v[120:123], v[166:169], v[174:177], v[120:123]
	v_mfma_f32_16x16x32_bf16 v[116:119], v[158:161], v[182:185], v[116:119]
	v_mfma_f32_16x16x32_bf16 v[112:115], v[166:169], v[182:185], v[112:115]
	v_mfma_f32_16x16x32_bf16 v[108:111], v[158:161], v[190:193], v[108:111]
	v_mfma_f32_16x16x32_bf16 v[104:107], v[166:169], v[190:193], v[104:107]
	v_mfma_f32_16x16x32_bf16 v[100:103], v[158:161], v[198:201], v[100:103]
	v_mfma_f32_16x16x32_bf16 v[96:99], v[166:169], v[198:201], v[96:99]
	v_mfma_f32_16x16x32_bf16 v[124:127], v[162:165], v[178:181], v[124:127]
	v_mfma_f32_16x16x32_bf16 v[120:123], v[170:173], v[178:181], v[120:123]
	v_mfma_f32_16x16x32_bf16 v[116:119], v[162:165], v[186:189], v[116:119]
	v_mfma_f32_16x16x32_bf16 v[112:115], v[170:173], v[186:189], v[112:115]
	v_mfma_f32_16x16x32_bf16 v[108:111], v[162:165], v[194:197], v[108:111]
	v_mfma_f32_16x16x32_bf16 v[104:107], v[170:173], v[194:197], v[104:107]
	v_mfma_f32_16x16x32_bf16 v[100:103], v[162:165], v[202:205], v[100:103]
	v_mfma_f32_16x16x32_bf16 v[96:99], v[170:173], v[202:205], v[96:99]
	s_nop 0
	s_barrier
	s_add_u32 s20, s19, 0x180
	s_addc_u32 s21, s22, 0
	v_readfirstlane_b32 s19, v147
	v_lshl_add_u64 v[206:207], s[20:21], 0, v[128:129]
	s_mov_b32 m0, s19
	v_readfirstlane_b32 s19, v148
	ds_read_b128 v[214:217], v137
	ds_read_b128 v[218:221], v137 offset:1024
	ds_read_b128 v[222:225], v137 offset:2048
	ds_read_b128 v[226:229], v137 offset:3072
	global_load_lds_dwordx4 v[206:207], off
	v_lshl_add_u64 v[206:207], s[20:21], 0, v[130:131]
	s_mov_b32 m0, s19
	s_nop 0
	global_load_lds_dwordx4 v[206:207], off
	s_barrier
	s_waitcnt lgkmcnt(0)
	s_nop 0
	s_waitcnt lgkmcnt(0)
	v_mfma_f32_16x16x32_bf16 v[92:95], v[214:217], v[174:177], v[92:95]
	v_mfma_f32_16x16x32_bf16 v[88:91], v[222:225], v[174:177], v[88:91]
	v_mfma_f32_16x16x32_bf16 v[84:87], v[214:217], v[182:185], v[84:87]
	v_mfma_f32_16x16x32_bf16 v[80:83], v[222:225], v[182:185], v[80:83]
	v_mfma_f32_16x16x32_bf16 v[76:79], v[214:217], v[190:193], v[76:79]
	v_mfma_f32_16x16x32_bf16 v[72:75], v[222:225], v[190:193], v[72:75]
	v_mfma_f32_16x16x32_bf16 v[68:71], v[214:217], v[198:201], v[68:71]
	v_mfma_f32_16x16x32_bf16 v[64:67], v[222:225], v[198:201], v[64:67]
	v_mfma_f32_16x16x32_bf16 v[92:95], v[218:221], v[178:181], v[92:95]
	v_mfma_f32_16x16x32_bf16 v[88:91], v[226:229], v[178:181], v[88:91]
	v_mfma_f32_16x16x32_bf16 v[84:87], v[218:221], v[186:189], v[84:87]
	v_mfma_f32_16x16x32_bf16 v[80:83], v[226:229], v[186:189], v[80:83]
	v_mfma_f32_16x16x32_bf16 v[76:79], v[218:221], v[194:197], v[76:79]
	v_mfma_f32_16x16x32_bf16 v[72:75], v[226:229], v[194:197], v[72:75]
	v_mfma_f32_16x16x32_bf16 v[68:71], v[218:221], v[202:205], v[68:71]
	v_mfma_f32_16x16x32_bf16 v[64:67], v[226:229], v[202:205], v[64:67]
	s_nop 0
	s_add_u32 s20, s23, 0x180
	s_addc_u32 s21, s24, 0
	v_readfirstlane_b32 s19, v149
	v_lshl_add_u64 v[206:207], s[20:21], 0, v[128:129]
	s_mov_b32 m0, s19
	v_readfirstlane_b32 s19, v150
	s_barrier
; #define LDA(dst, b, h) for (int m = 0; m < 4; ++m) for (int k = 0; k < 2; ++k) \
;     dst[m][k] = *reinterpret_cast<const bf16x8*>((char*)SA(b, h) + lds_byte(wr * 64 + m * 16 + fr, k * 32 + fq * 8))
; #define LDB(dst, b, h) for (int n = 0; n < 2; ++n) for (int k = 0; k < 2; ++k) \
;     dst[n][k] = *reinterpret_cast<const bf16x8*>((char*)SB(b, h) + lds_byte(wc * 32 + n * 16 + fr, k * 32 + fq * 8))
; #define WAIT_V(n) asm volatile("s_waitcnt vmcnt(" #n ")" ::: "memory")
; #define WAIT_L(n) asm volatile("s_waitcnt lgkmcnt(" #n ")" ::: "memory")
; #define BAR __builtin_amdgcn_s_barrier()
; #define SCHED __builtin_amdgcn_sched_barrier(0)
; template <bool SWAP, int lda, int ldb, int K>
; __device__ __forceinline__ void gemm256(const bf16_t* __restrict__ Ap, const bf16_t* __restrict__ Bp, f32x4 (&acc)[2][2][4][2]) {
;     ...
;         LDB(B0, 1, 0); SCHED; LDA(At, 1, 0); STAGE(SA(0, 1), Ap, lda, HALF, t + 2);
;         WAIT_L(8); BAR; WAIT_L(0); MMA(0, 0, At, B0); BAR; SCHED;
;         LDB(B1, 1, 1); STAGE(SB(1, 0), Bp, ldb, 0, t + 3);
;         BAR; WAIT_L(0); MMA(0, 1, At, B1); BAR;
;         LDA(At, 1, 1); STAGE(SA(1, 0), Ap, lda, 0, t + 3);
;         BAR; WAIT_L(0); MMA(1, 0, At, B0); BAR; SCHED;
;         STAGE(SB(1, 1), Bp, ldb, HALF, t + 3);
;         WAIT_V(6); BAR; MMA(1, 1, At, B1); BAR;
;     }
;     { LDB(B0, 0, 0); LDA(At, 0, 0); STAGE(SA(1, 1), Ap, lda, HALF, nt - 1);
;       BAR; WAIT_L(0); MMA(0, 0, At, B0); BAR;
;       LDB(B1, 0, 1); BAR; WAIT_L(0); MMA(0, 1, At, B1); BAR;
;       LDA(At, 0, 1); WAIT_V(4); BAR; WAIT_L(0); MMA(1, 0, At, B0); MMA(1, 1, At, B1); BAR; }
	ds_read_b128 v[174:177], v136 offset:49152
	ds_read_b128 v[178:181], v136 offset:50176
	ds_read_b128 v[182:185], v135 offset:49152
	ds_read_b128 v[186:189], v135 offset:50176
	ds_read_b128 v[190:193], v134 offset:49152
	ds_read_b128 v[194:197], v134 offset:50176
	ds_read_b128 v[198:201], v133 offset:49152
	ds_read_b128 v[202:205], v133 offset:50176
	global_load_lds_dwordx4 v[206:207], off
	v_lshl_add_u64 v[206:207], s[20:21], 0, v[130:131]
	s_mov_b32 m0, s19
	s_nop 0
	global_load_lds_dwordx4 v[206:207], off
	s_barrier
	s_waitcnt lgkmcnt(0)
	s_nop 0
	s_waitcnt lgkmcnt(0)
	v_mfma_f32_16x16x32_bf16 v[60:63], v[158:161], v[174:177], v[60:63]
	v_mfma_f32_16x16x32_bf16 v[56:59], v[166:169], v[174:177], v[56:59]
	v_mfma_f32_16x16x32_bf16 v[52:55], v[158:161], v[182:185], v[52:55]
	v_mfma_f32_16x16x32_bf16 v[48:51], v[166:169], v[182:185], v[48:51]
	v_mfma_f32_16x16x32_bf16 v[44:47], v[158:161], v[190:193], v[44:47]
	v_mfma_f32_16x16x32_bf16 v[40:43], v[166:169], v[190:193], v[40:43]
	v_mfma_f32_16x16x32_bf16 v[36:39], v[158:161], v[198:201], v[36:39]
	v_mfma_f32_16x16x32_bf16 v[32:35], v[166:169], v[198:201], v[32:35]
	v_mfma_f32_16x16x32_bf16 v[60:63], v[162:165], v[178:181], v[60:63]
	v_mfma_f32_16x16x32_bf16 v[56:59], v[170:173], v[178:181], v[56:59]
	v_mfma_f32_16x16x32_bf16 v[52:55], v[162:165], v[186:189], v[52:55]
	v_mfma_f32_16x16x32_bf16 v[48:51], v[170:173], v[186:189], v[48:51]
	v_mfma_f32_16x16x32_bf16 v[44:47], v[162:165], v[194:197], v[44:47]
	v_mfma_f32_16x16x32_bf16 v[40:43], v[170:173], v[194:197], v[40:43]
	v_mfma_f32_16x16x32_bf16 v[36:39], v[162:165], v[202:205], v[36:39]
	v_mfma_f32_16x16x32_bf16 v[32:35], v[170:173], v[202:205], v[32:35]
	s_nop 0
	s_barrier
	s_add_u32 s20, s25, 0x180
	s_addc_u32 s21, s26, 0
	v_readfirstlane_b32 s19, v152
	v_lshl_add_u64 v[158:159], s[20:21], 0, v[128:129]
	s_mov_b32 m0, s19
	v_readfirstlane_b32 s19, v153
	global_load_lds_dwordx4 v[158:159], off
	v_lshl_add_u64 v[158:159], s[20:21], 0, v[130:131]
	s_mov_b32 m0, s19
	s_nop 0
	global_load_lds_dwordx4 v[158:159], off
	s_waitcnt vmcnt(6)
	s_barrier
	s_nop 0
	v_mfma_f32_16x16x32_bf16 v[28:31], v[214:217], v[174:177], v[28:31]
	v_mfma_f32_16x16x32_bf16 v[24:27], v[222:225], v[174:177], v[24:27]
	v_mfma_f32_16x16x32_bf16 v[20:23], v[214:217], v[182:185], v[20:23]
	v_mfma_f32_16x16x32_bf16 v[16:19], v[222:225], v[182:185], v[16:19]
	v_mfma_f32_16x16x32_bf16 v[12:15], v[214:217], v[190:193], v[12:15]
	v_mfma_f32_16x16x32_bf16 v[8:11], v[222:225], v[190:193], v[8:11]
	v_mfma_f32_16x16x32_bf16 v[4:7], v[214:217], v[198:201], v[4:7]
	v_mfma_f32_16x16x32_bf16 v[0:3], v[222:225], v[198:201], v[0:3]
	v_mfma_f32_16x16x32_bf16 v[28:31], v[218:221], v[178:181], v[28:31]
	v_mfma_f32_16x16x32_bf16 v[24:27], v[226:229], v[178:181], v[24:27]
	v_mfma_f32_16x16x32_bf16 v[20:23], v[218:221], v[186:189], v[20:23]
	v_mfma_f32_16x16x32_bf16 v[16:19], v[226:229], v[186:189], v[16:19]
	v_mfma_f32_16x16x32_bf16 v[12:15], v[218:221], v[194:197], v[12:15]
	v_mfma_f32_16x16x32_bf16 v[8:11], v[226:229], v[194:197], v[8:11]
	v_mfma_f32_16x16x32_bf16 v[4:7], v[218:221], v[202:205], v[4:7]
	v_mfma_f32_16x16x32_bf16 v[0:3], v[226:229], v[202:205], v[0:3]
	s_nop 0
	s_add_i32 s18, s18, 2
	s_add_u32 s0, s0, 0x100
	s_addc_u32 s1, s1, 0
	s_cmp_lt_u32 s18, 12
	s_barrier
	s_cbranch_scc1 .LBB0_460
	s_add_u32 s0, s2, 0x40780
	s_addc_u32 s1, s3, 0
	v_readfirstlane_b32 s2, v155
	v_lshl_add_u64 v[148:149], s[0:1], 0, v[128:129]
	s_mov_b32 m0, s2
	v_lshl_add_u64 v[130:131], s[0:1], 0, v[130:131]
	v_readfirstlane_b32 s0, v156
	ds_read_b128 v[138:141], v154
	ds_read_b128 v[144:147], v154 offset:1024
	ds_read_b128 v[158:161], v154 offset:2048
	ds_read_b128 v[162:165], v154 offset:3072
	ds_read_b128 v[166:169], v136
	ds_read_b128 v[170:173], v136 offset:1024
	ds_read_b128 v[174:177], v135
	ds_read_b128 v[178:181], v135 offset:1024
	ds_read_b128 v[182:185], v134
	ds_read_b128 v[186:189], v134 offset:1024
	ds_read_b128 v[190:193], v133
	ds_read_b128 v[194:197], v133 offset:1024
	global_load_lds_dwordx4 v[148:149], off
	s_mov_b32 m0, s0
	s_nop 0
	global_load_lds_dwordx4 v[130:131], off
	s_barrier
	s_waitcnt lgkmcnt(0)
	s_nop 0
	s_waitcnt lgkmcnt(0)
	v_mfma_f32_16x16x32_bf16 v[124:127], v[138:141], v[166:169], v[124:127]
	v_mfma_f32_16x16x32_bf16 v[120:123], v[158:161], v[166:169], v[120:123]
	v_mfma_f32_16x16x32_bf16 v[116:119], v[138:141], v[174:177], v[116:119]
	v_mfma_f32_16x16x32_bf16 v[112:115], v[158:161], v[174:177], v[112:115]
	v_mfma_f32_16x16x32_bf16 v[108:111], v[138:141], v[182:185], v[108:111]
	v_mfma_f32_16x16x32_bf16 v[124:127], v[144:147], v[170:173], v[124:127]
	v_mfma_f32_16x16x32_bf16 v[120:123], v[162:165], v[170:173], v[120:123]
	v_mfma_f32_16x16x32_bf16 v[116:119], v[144:147], v[178:181], v[116:119]
	v_mfma_f32_16x16x32_bf16 v[112:115], v[162:165], v[178:181], v[112:115]
	v_mfma_f32_16x16x32_bf16 v[108:111], v[144:147], v[186:189], v[108:111]
	v_mfma_f32_16x16x32_bf16 v[104:107], v[158:161], v[182:185], v[104:107]
	v_mfma_f32_16x16x32_bf16 v[100:103], v[138:141], v[190:193], v[100:103]
	v_mfma_f32_16x16x32_bf16 v[96:99], v[158:161], v[190:193], v[96:99]
	v_mfma_f32_16x16x32_bf16 v[152:155], v[162:165], v[186:189], v[104:107]
	v_mfma_f32_16x16x32_bf16 v[198:201], v[144:147], v[194:197], v[100:103]
	v_mfma_f32_16x16x32_bf16 v[202:205], v[162:165], v[194:197], v[96:99]
	s_nop 0
	s_barrier
	s_nop 2
	ds_read_b128 v[96:99], v151
	ds_read_b128 v[100:103], v151 offset:1024
	ds_read_b128 v[104:107], v151 offset:2048
	ds_read_b128 v[148:151], v151 offset:3072
	s_barrier
; #define LDA(dst, b, h) for (int m = 0; m < 4; ++m) for (int k = 0; k < 2; ++k) \
;     dst[m][k] = *reinterpret_cast<const bf16x8*>((char*)SA(b, h) + lds_byte(wr * 64 + m * 16 + fr, k * 32 + fq * 8))
; #define LDB(dst, b, h) for (int n = 0; n < 2; ++n) for (int k = 0; k < 2; ++k) \
;     dst[n][k] = *reinterpret_cast<const bf16x8*>((char*)SB(b, h) + lds_byte(wc * 32 + n * 16 + fr, k * 32 + fq * 8))
; #define WAIT_V(n) asm volatile("s_waitcnt vmcnt(" #n ")" ::: "memory")
; #define WAIT_L(n) asm volatile("s_waitcnt lgkmcnt(" #n ")" ::: "memory")
; #define BAR __builtin_amdgcn_s_barrier()
; template <bool SWAP, int lda, int ldb, int K>
; __device__ __forceinline__ void gemm256(const bf16_t* __restrict__ Ap, const bf16_t* __restrict__ Bp, f32x4 (&acc)[2][2][4][2]) {
;     ...
;       BAR; WAIT_L(0); MMA(0, 0, At, B0); BAR;
;       LDB(B1, 0, 1); BAR; WAIT_L(0); MMA(0, 1, At, B1); BAR;
;       LDA(At, 0, 1); WAIT_V(4); BAR; WAIT_L(0); MMA(1, 0, At, B0); MMA(1, 1, At, B1); BAR; }
;     { LDB(B0, 1, 0); LDA(At, 1, 0); WAIT_V(2); BAR; WAIT_L(0); MMA(0, 0, At, B0); BAR;
;       LDB(B1, 1, 1); WAIT_V(0); BAR; WAIT_L(0); MMA(0, 1, At, B1); BAR;
;       LDA(At, 1, 1); BAR; WAIT_L(0); MMA(1, 0, At, B0); MMA(1, 1, At, B1); BAR; }
	s_waitcnt lgkmcnt(0)
	s_nop 0
	s_waitcnt lgkmcnt(0)
	v_mfma_f32_16x16x32_bf16 v[92:95], v[96:99], v[166:169], v[92:95]
	v_mfma_f32_16x16x32_bf16 v[84:87], v[96:99], v[174:177], v[84:87]
	v_mfma_f32_16x16x32_bf16 v[80:83], v[104:107], v[174:177], v[80:83]
	v_mfma_f32_16x16x32_bf16 v[76:79], v[96:99], v[182:185], v[76:79]
	v_mfma_f32_16x16x32_bf16 v[64:67], v[104:107], v[190:193], v[64:67]
	v_mfma_f32_16x16x32_bf16 v[92:95], v[100:103], v[170:173], v[92:95]
	v_mfma_f32_16x16x32_bf16 v[88:91], v[104:107], v[166:169], v[88:91]
	v_mfma_f32_16x16x32_bf16 v[84:87], v[100:103], v[178:181], v[84:87]
	v_mfma_f32_16x16x32_bf16 v[80:83], v[148:151], v[178:181], v[80:83]
	v_mfma_f32_16x16x32_bf16 v[76:79], v[100:103], v[186:189], v[76:79]
	v_mfma_f32_16x16x32_bf16 v[72:75], v[104:107], v[182:185], v[72:75]
	v_mfma_f32_16x16x32_bf16 v[68:71], v[96:99], v[190:193], v[68:71]
	v_mfma_f32_16x16x32_bf16 v[64:67], v[148:151], v[194:197], v[64:67]
	v_mfma_f32_16x16x32_bf16 v[166:169], v[148:151], v[170:173], v[88:91]
	v_mfma_f32_16x16x32_bf16 v[170:173], v[148:151], v[186:189], v[72:75]
	v_mfma_f32_16x16x32_bf16 v[174:177], v[100:103], v[194:197], v[68:71]
	s_nop 0
	s_barrier
	s_nop 1
	ds_read_b128 v[68:71], v136 offset:16384
	ds_read_b128 v[72:75], v136 offset:17408
	ds_read_b128 v[88:91], v135 offset:16384
	ds_read_b128 v[178:181], v135 offset:17408
	ds_read_b128 v[182:185], v134 offset:16384
	ds_read_b128 v[186:189], v134 offset:17408
	ds_read_b128 v[190:193], v133 offset:16384
	ds_read_b128 v[194:197], v133 offset:17408
	s_waitcnt vmcnt(4)
	s_barrier
	s_waitcnt lgkmcnt(0)
	s_nop 0
	s_waitcnt lgkmcnt(0)
	v_mfma_f32_16x16x32_bf16 v[52:55], v[138:141], v[88:91], v[52:55]
	v_mfma_f32_16x16x32_bf16 v[48:51], v[158:161], v[88:91], v[48:51]
	v_mfma_f32_16x16x32_bf16 v[44:47], v[138:141], v[182:185], v[44:47]
	v_mfma_f32_16x16x32_bf16 v[40:43], v[158:161], v[182:185], v[40:43]
	v_mfma_f32_16x16x32_bf16 v[36:39], v[138:141], v[190:193], v[36:39]
	v_mfma_f32_16x16x32_bf16 v[32:35], v[158:161], v[190:193], v[32:35]
	v_mfma_f32_16x16x32_bf16 v[60:63], v[138:141], v[68:71], v[60:63]
	v_mfma_f32_16x16x32_bf16 v[56:59], v[158:161], v[68:71], v[56:59]
	v_mfma_f32_16x16x32_bf16 v[52:55], v[144:147], v[178:181], v[52:55]
	v_mfma_f32_16x16x32_bf16 v[48:51], v[162:165], v[178:181], v[48:51]
	v_mfma_f32_16x16x32_bf16 v[44:47], v[144:147], v[186:189], v[44:47]
	v_mfma_f32_16x16x32_bf16 v[40:43], v[162:165], v[186:189], v[40:43]
	v_mfma_f32_16x16x32_bf16 v[36:39], v[144:147], v[194:197], v[36:39]
	v_mfma_f32_16x16x32_bf16 v[32:35], v[162:165], v[194:197], v[32:35]
	v_mfma_f32_16x16x32_bf16 v[214:217], v[144:147], v[72:75], v[60:63]
	v_mfma_f32_16x16x32_bf16 v[218:221], v[162:165], v[72:75], v[56:59]
	s_nop 0
	s_nop 0
	v_mfma_f32_16x16x32_bf16 v[28:31], v[96:99], v[68:71], v[28:31]
	v_mfma_f32_16x16x32_bf16 v[24:27], v[104:107], v[68:71], v[24:27]
	v_mfma_f32_16x16x32_bf16 v[20:23], v[96:99], v[88:91], v[20:23]
	v_mfma_f32_16x16x32_bf16 v[16:19], v[104:107], v[88:91], v[16:19]
	v_mfma_f32_16x16x32_bf16 v[12:15], v[96:99], v[182:185], v[12:15]
	v_mfma_f32_16x16x32_bf16 v[8:11], v[104:107], v[182:185], v[8:11]
	v_mfma_f32_16x16x32_bf16 v[4:7], v[96:99], v[190:193], v[4:7]
	v_mfma_f32_16x16x32_bf16 v[0:3], v[104:107], v[190:193], v[0:3]
	v_mfma_f32_16x16x32_bf16 v[28:31], v[100:103], v[72:75], v[28:31]
	v_mfma_f32_16x16x32_bf16 v[24:27], v[148:151], v[72:75], v[24:27]
	v_mfma_f32_16x16x32_bf16 v[20:23], v[100:103], v[178:181], v[20:23]
	v_mfma_f32_16x16x32_bf16 v[16:19], v[148:151], v[178:181], v[16:19]
	v_mfma_f32_16x16x32_bf16 v[12:15], v[100:103], v[186:189], v[12:15]
	v_mfma_f32_16x16x32_bf16 v[8:11], v[148:151], v[186:189], v[8:11]
	v_mfma_f32_16x16x32_bf16 v[4:7], v[100:103], v[194:197], v[4:7]
	v_mfma_f32_16x16x32_bf16 v[0:3], v[148:151], v[194:197], v[0:3]
	s_nop 0
	s_barrier
	ds_read_b128 v[138:141], v142
	ds_read_b128 v[144:147], v142 offset:1024
	ds_read_b128 v[148:151], v142 offset:2048
	ds_read_b128 v[156:159], v142 offset:3072
	ds_read_b128 v[56:59], v136 offset:32768
	ds_read_b128 v[60:63], v136 offset:33792
	ds_read_b128 v[68:71], v135 offset:32768
	ds_read_b128 v[72:75], v135 offset:33792
	ds_read_b128 v[160:163], v134 offset:32768
	ds_read_b128 v[178:181], v134 offset:33792
	ds_read_b128 v[182:185], v133 offset:32768
	ds_read_b128 v[186:189], v133 offset:33792
	s_waitcnt vmcnt(2)
	s_barrier
	s_waitcnt lgkmcnt(0)
	s_nop 0
	s_waitcnt lgkmcnt(0)
	v_mfma_f32_16x16x32_bf16 v[88:91], v[138:141], v[56:59], v[124:127]
	v_mfma_f32_16x16x32_bf16 v[124:127], v[144:147], v[60:63], v[88:91]
	v_mfma_f32_16x16x32_bf16 v[88:91], v[148:151], v[56:59], v[120:123]
	v_mfma_f32_16x16x32_bf16 v[120:123], v[156:159], v[60:63], v[88:91]
	v_mfma_f32_16x16x32_bf16 v[88:91], v[138:141], v[68:71], v[116:119]
	v_mfma_f32_16x16x32_bf16 v[116:119], v[144:147], v[72:75], v[88:91]
	v_mfma_f32_16x16x32_bf16 v[88:91], v[148:151], v[68:71], v[112:115]
	v_mfma_f32_16x16x32_bf16 v[112:115], v[156:159], v[72:75], v[88:91]
	v_mfma_f32_16x16x32_bf16 v[88:91], v[138:141], v[160:163], v[108:111]
	v_mfma_f32_16x16x32_bf16 v[104:107], v[144:147], v[178:181], v[88:91]
	v_mfma_f32_16x16x32_bf16 v[88:91], v[148:151], v[160:163], v[152:155]
	v_mfma_f32_16x16x32_bf16 v[100:103], v[156:159], v[178:181], v[88:91]
	v_mfma_f32_16x16x32_bf16 v[88:91], v[138:141], v[182:185], v[198:201]
	v_mfma_f32_16x16x32_bf16 v[96:99], v[144:147], v[186:189], v[88:91]
	v_mfma_f32_16x16x32_bf16 v[88:91], v[148:151], v[182:185], v[202:205]
	v_mfma_f32_16x16x32_bf16 v[88:91], v[156:159], v[186:189], v[88:91]
	s_nop 0
	s_barrier
	ds_read_b128 v[152:155], v137
	ds_read_b128 v[190:193], v137 offset:1024
	ds_read_b128 v[194:197], v137 offset:2048
	ds_read_b128 v[198:201], v137 offset:3072
	s_waitcnt vmcnt(0)
	s_barrier
; __device__ __forceinline__ int tid_opaque() { int t = threadIdx.x; asm volatile("" : "+v"(t)); return t; }
; #define LDA(dst, b, h) for (int m = 0; m < 4; ++m) for (int k = 0; k < 2; ++k) \
;     dst[m][k] = *reinterpret_cast<const bf16x8*>((char*)SA(b, h) + lds_byte(wr * 64 + m * 16 + fr, k * 32 + fq * 8))
; #define LDB(dst, b, h) for (int n = 0; n < 2; ++n) for (int k = 0; k < 2; ++k) \
;     dst[n][k] = *reinterpret_cast<const bf16x8*>((char*)SB(b, h) + lds_byte(wc * 32 + n * 16 + fr, k * 32 + fq * 8))
; #define WAIT_V(n) asm volatile("s_waitcnt vmcnt(" #n ")" ::: "memory")
; #define WAIT_L(n) asm volatile("s_waitcnt lgkmcnt(" #n ")" ::: "memory")
; #define BAR __builtin_amdgcn_s_barrier()
; #define SCHED __builtin_amdgcn_sched_barrier(0)
; template <bool SWAP, int lda, int ldb, int K>
; __device__ __forceinline__ void gemm256(const bf16_t* __restrict__ Ap, const bf16_t* __restrict__ Bp, f32x4 (&acc)[2][2][4][2]) {
;     ...
;     { LDB(B0, 1, 0); LDA(At, 1, 0); WAIT_V(2); BAR; WAIT_L(0); MMA(0, 0, At, B0); BAR;
;       LDB(B1, 1, 1); WAIT_V(0); BAR; WAIT_L(0); MMA(0, 1, At, B1); BAR;
;       LDA(At, 1, 1); BAR; WAIT_L(0); MMA(1, 0, At, B0); MMA(1, 1, At, B1); BAR; }
;     if (wr == 0) BAR;
;     SCHED;
; __device__ __forceinline__ void phase_D(const Params& p, int l) {
;     ...
;             const int et = tid_opaque();
;             const int wr = (et >> 8) & 1, wc = (et >> 6) & 3, fr = et & 15, fq = (et >> 4) & 3;
; #pragma unroll
;             for (int ai = 0; ai < 2; ++ai)
; #pragma unroll
;                 for (int m = 0; m < 4; ++m) {
;                     int row = brow + ai * 128 + wr * 64 + m * 16 + fr;
;                     float ss = 0.f;
; #pragma unroll
;                     for (int bj = 0; bj < 2; ++bj)
; #pragma unroll
;                         for (int n = 0; n < 2; ++n) {
;                             f32x4 a = acc[ai][bj][m][n];
;                             ss += a[0] * a[0] + a[1] * a[1] + a[2] * a[2] + a[3] * a[3];
;                         }
;                     ss += __shfl_xor(ss, 16);
;                     ss += __shfl_xor(ss, 32);
;                     if (fq == 0) PART[(long)row * 16 + pn * 4 + wc] = ss;
	s_waitcnt lgkmcnt(0)
	s_nop 0
	s_waitcnt lgkmcnt(0)
	v_mfma_f32_16x16x32_bf16 v[92:95], v[152:155], v[56:59], v[92:95]
	v_mfma_f32_16x16x32_bf16 v[56:59], v[194:197], v[56:59], v[166:169]
	v_mfma_f32_16x16x32_bf16 v[108:111], v[190:193], v[60:63], v[92:95]
	v_mfma_f32_16x16x32_bf16 v[92:95], v[198:201], v[60:63], v[56:59]
	v_mfma_f32_16x16x32_bf16 v[56:59], v[152:155], v[68:71], v[84:87]
	v_mfma_f32_16x16x32_bf16 v[84:87], v[190:193], v[72:75], v[56:59]
	v_mfma_f32_16x16x32_bf16 v[56:59], v[194:197], v[68:71], v[80:83]
	v_mfma_f32_16x16x32_bf16 v[80:83], v[198:201], v[72:75], v[56:59]
	v_mfma_f32_16x16x32_bf16 v[56:59], v[152:155], v[160:163], v[76:79]
	v_mfma_f32_16x16x32_bf16 v[72:75], v[190:193], v[178:181], v[56:59]
	v_mfma_f32_16x16x32_bf16 v[56:59], v[194:197], v[160:163], v[170:173]
	v_mfma_f32_16x16x32_bf16 v[68:71], v[198:201], v[178:181], v[56:59]
	v_mfma_f32_16x16x32_bf16 v[56:59], v[152:155], v[182:185], v[174:177]
	v_mfma_f32_16x16x32_bf16 v[60:63], v[190:193], v[186:189], v[56:59]
	v_mfma_f32_16x16x32_bf16 v[56:59], v[194:197], v[182:185], v[64:67]
	v_mfma_f32_16x16x32_bf16 v[56:59], v[198:201], v[186:189], v[56:59]
	s_nop 0
	s_barrier
	ds_read_b128 v[160:163], v136 offset:49152
	ds_read_b128 v[164:167], v136 offset:50176
	ds_read_b128 v[168:171], v135 offset:49152
	ds_read_b128 v[172:175], v135 offset:50176
	ds_read_b128 v[176:179], v134 offset:49152
	ds_read_b128 v[134:137], v134 offset:50176
	ds_read_b128 v[180:183], v133 offset:49152
	ds_read_b128 v[184:187], v133 offset:50176
	s_barrier
	s_waitcnt lgkmcnt(0)
	s_nop 0
	s_waitcnt lgkmcnt(0)
	v_mfma_f32_16x16x32_bf16 v[64:67], v[138:141], v[160:163], v[214:217]
	v_mfma_f32_16x16x32_bf16 v[76:79], v[144:147], v[164:167], v[64:67]
	v_mfma_f32_16x16x32_bf16 v[64:67], v[148:151], v[160:163], v[218:221]
	v_mfma_f32_16x16x32_bf16 v[52:55], v[138:141], v[168:171], v[52:55]
	v_mfma_f32_16x16x32_bf16 v[48:51], v[148:151], v[168:171], v[48:51]
	v_mfma_f32_16x16x32_bf16 v[44:47], v[138:141], v[176:179], v[44:47]
	v_mfma_f32_16x16x32_bf16 v[40:43], v[148:151], v[176:179], v[40:43]
	v_mfma_f32_16x16x32_bf16 v[36:39], v[138:141], v[180:183], v[36:39]
	v_mfma_f32_16x16x32_bf16 v[32:35], v[148:151], v[180:183], v[32:35]
	v_mfma_f32_16x16x32_bf16 v[64:67], v[156:159], v[164:167], v[64:67]
	v_mfma_f32_16x16x32_bf16 v[52:55], v[144:147], v[172:175], v[52:55]
	v_mfma_f32_16x16x32_bf16 v[48:51], v[156:159], v[172:175], v[48:51]
	v_mfma_f32_16x16x32_bf16 v[44:47], v[144:147], v[134:137], v[44:47]
	v_mfma_f32_16x16x32_bf16 v[40:43], v[156:159], v[134:137], v[40:43]
	v_mfma_f32_16x16x32_bf16 v[36:39], v[144:147], v[184:187], v[36:39]
	v_mfma_f32_16x16x32_bf16 v[32:35], v[156:159], v[184:187], v[32:35]
	s_nop 0
	s_nop 0
	v_mfma_f32_16x16x32_bf16 v[28:31], v[152:155], v[160:163], v[28:31]
	v_mfma_f32_16x16x32_bf16 v[24:27], v[194:197], v[160:163], v[24:27]
	v_mfma_f32_16x16x32_bf16 v[20:23], v[152:155], v[168:171], v[20:23]
	v_mfma_f32_16x16x32_bf16 v[16:19], v[194:197], v[168:171], v[16:19]
	v_mfma_f32_16x16x32_bf16 v[12:15], v[152:155], v[176:179], v[12:15]
	v_mfma_f32_16x16x32_bf16 v[8:11], v[194:197], v[176:179], v[8:11]
	v_mfma_f32_16x16x32_bf16 v[4:7], v[152:155], v[180:183], v[4:7]
	v_mfma_f32_16x16x32_bf16 v[0:3], v[194:197], v[180:183], v[0:3]
	v_mfma_f32_16x16x32_bf16 v[28:31], v[190:193], v[164:167], v[28:31]
	v_mfma_f32_16x16x32_bf16 v[24:27], v[198:201], v[164:167], v[24:27]
	v_mfma_f32_16x16x32_bf16 v[20:23], v[190:193], v[172:175], v[20:23]
	v_mfma_f32_16x16x32_bf16 v[16:19], v[198:201], v[172:175], v[16:19]
	v_mfma_f32_16x16x32_bf16 v[12:15], v[190:193], v[134:137], v[12:15]
	v_mfma_f32_16x16x32_bf16 v[8:11], v[198:201], v[134:137], v[8:11]
	v_mfma_f32_16x16x32_bf16 v[4:7], v[190:193], v[184:187], v[4:7]
	v_mfma_f32_16x16x32_bf16 v[0:3], v[198:201], v[184:187], v[0:3]
	s_nop 0
	v_cmp_gt_u32_e32 vcc, s91, v132
	s_barrier
	s_and_saveexec_b64 s[0:1], vcc
	s_cbranch_execz .LBB0_463
	s_barrier
.LBB0_463:
	s_or_b64 exec, exec, s[0:1]
	s_setprio 0
	v_mov_b32_e32 v128, v208
	v_and_b32_e32 v132, 64, v213
	v_lshrrev_b32_e32 v131, 2, v128
	v_and_b32_e32 v130, 15, v128
	v_and_b32_e32 v131, 64, v131
	v_or3_b32 v130, v130, v131, s6
	v_xor_b32_e32 v131, 16, v213
	v_add_u32_e32 v132, 64, v132
	v_cmp_lt_i32_e32 vcc, v131, v132
	s_lshl_b32 s0, s15, 2
	s_ashr_i32 s1, s0, 31
	v_cndmask_b32_e32 v131, v213, v131, vcc
	v_lshlrev_b32_e32 v134, 2, v131
	v_xor_b32_e32 v131, 32, v213
	v_cmp_lt_i32_e32 vcc, v131, v132
	v_mul_f32_e32 v132, v121, v121
	v_fmac_f32_e32 v132, v120, v120
	v_cndmask_b32_e32 v131, v213, v131, vcc
	v_lshlrev_b32_e32 v135, 2, v131
	v_and_b32_e32 v131, 48, v128
	v_cmp_eq_u32_e32 vcc, 0, v131
	v_mul_f32_e32 v131, v125, v125
	v_fmac_f32_e32 v131, v124, v124
	v_fmac_f32_e32 v131, v126, v126
	v_fmac_f32_e32 v132, v122, v122
	v_fmac_f32_e32 v131, v127, v127
	v_fmac_f32_e32 v132, v123, v123
	v_add_f32_e32 v131, v131, v132
	v_mul_f32_e32 v132, v109, v109
	v_fmac_f32_e32 v132, v108, v108
	v_fmac_f32_e32 v132, v110, v110
	v_fmac_f32_e32 v132, v111, v111
	v_add_f32_e32 v131, v131, v132
	v_mul_f32_e32 v132, v93, v93
	v_fmac_f32_e32 v132, v92, v92
	v_fmac_f32_e32 v132, v94, v94
	v_fmac_f32_e32 v132, v95, v95
	v_add_f32_e32 v131, v131, v132
	ds_bpermute_b32 v132, v134, v131
	s_lshl_b64 s[0:1], s[0:1], 2
	s_add_u32 s0, s96, s0
	v_lshrrev_b32_e32 v128, 4, v128
	s_addc_u32 s1, s97, s1
	s_waitcnt lgkmcnt(0)
	v_add_f32_e32 v136, v131, v132
	ds_bpermute_b32 v137, v135, v136
	v_and_b32_e32 v128, 12, v128
	v_lshl_add_u64 v[132:133], s[0:1], 0, v[128:129]
	s_and_saveexec_b64 s[0:1], vcc
	s_cbranch_execz .LBB0_465
	v_ashrrev_i32_e32 v131, 31, v130
	v_lshlrev_b64 v[138:139], 6, v[130:131]
	v_lshl_add_u64 v[138:139], v[132:133], 0, v[138:139]
	s_waitcnt lgkmcnt(0)
	v_add_f32_e32 v128, v136, v137
	global_store_dword v[138:139], v128, off
